# v100: v95 + the redundant s_waitcnt lgkmcnt(0) at the head of every MFMA segment of the GEMM K loops removed (it repeats the one in front of the barrier)
# speedup vs baseline: 1.0063x; 1.0063x over previous
; #define PG8_STAGE(bufoff, gbase, voff) do { _Pragma("unroll") for (int _i = 0; _i < 2; ++_i) \
;         __builtin_amdgcn_global_load_lds((const unsigned*)((const char*)(gbase) + (voff)[_i]), (PG8_LAS unsigned*)(lds + (bufoff) + ldsw + _i * 8192), 16, 0, 0); } while (0)
; #define PG8_LDA(dst, b, h) do { _Pragma("unroll") for (int m = 0; m < 4; ++m) _Pragma("unroll") for (int k = 0; k < 2; ++k) dst[m][k] = *(const PG8_LAS bf16x8*)(lds + PG8_SA(b, h) + aoff + m * 2048 + k * 1024); } while (0)
; #define PG8_LDB(dst, b, h) do { _Pragma("unroll") for (int n = 0; n < 2; ++n) _Pragma("unroll") for (int k = 0; k < 2; ++k) dst[n][k] = *(const PG8_LAS bf16x8*)(lds + PG8_SB(b, h) + boff + n * 2048 + k * 1024); } while (0)
; #define PG8_MMA(ai, bj, At, Bt) do { __builtin_amdgcn_s_setprio(1); _Pragma("unroll") for (int m = 0; m < 4; ++m) _Pragma("unroll") for (int n = 0; n < 2; ++n) _Pragma("unroll") for (int k = 0; k < 2; ++k) \
;         acc[ai][bj][m][n] = __builtin_amdgcn_mfma_f32_16x16x32_bf16(Bt[n][k], At[m][k], acc[ai][bj][m][n], 0, 0, 0); __builtin_amdgcn_s_setprio(0); } while (0)
; #define PG8_BAR __builtin_amdgcn_s_barrier()
; template <class Epi, class Sched, bool ALIGN_EPI, int LMASK = -1, int LMASKB = LMASK>
; __device__ __forceinline__ void gemm_phase(PG8_LAS unsigned char* lds, const Gemm g, const Sched& S, const Epi& E) {
;     ...
;             PG8_LDB(B0, 0, 0); PG8_LDB(B1, 0, 1); PG8_SCHED; PG8_LDA(At, 0, 0); PG8_STAGE(PG8_SA(1, 1), a1 + hstepA, voffA);
;             PG8_WAIT_V(8); PG8_WAIT_L(0); PG8_BAR; PG8_MMA(0, 0, At, B0); PG8_MMA(0, 1, At, B1); PG8_BAR; PG8_SCHED;
;             PG8_LDA(At, 0, 1); PG8_STAGE(PG8_SB(0, 0), b2, voffB); PG8_STAGE(PG8_SB(0, 1), b2 + hstepB, voffB); PG8_STAGE(PG8_SA(0, 0), a2, voffA);
;             PG8_WAIT_V(8); PG8_WAIT_L(0); PG8_BAR; PG8_MMA(1, 0, At, B0); PG8_MMA(1, 1, At, B1); PG8_BAR; PG8_SCHED;
;             PG8_LDB(B0, 1, 0); PG8_LDB(B1, 1, 1); PG8_SCHED; PG8_LDA(At, 1, 0); PG8_STAGE(PG8_SA(0, 1), a2 + hstepA, voffA);
;             PG8_WAIT_V(8); PG8_WAIT_L(0); PG8_BAR; PG8_MMA(0, 0, At, B0); PG8_MMA(0, 1, At, B1); PG8_BAR; PG8_SCHED;
;             PG8_LDA(At, 1, 1); PG8_STAGE(PG8_SB(1, 0), b3, voffB); PG8_STAGE(PG8_SB(1, 1), b3 + hstepB, voffB); PG8_STAGE(PG8_SA(1, 0), a3, voffA);
;             PG8_WAIT_V(8); PG8_WAIT_L(0); PG8_BAR; PG8_MMA(1, 0, At, B0); PG8_MMA(1, 1, At, B1); PG8_BAR; PG8_SCHED;
.LBB0_206:
	s_ashr_i32 s17, s16, 31
	s_lshl_b64 s[2:3], s[16:17], 17
	s_add_u32 s20, s1, s2
	s_addc_u32 s21, s33, s3
	s_and_b64 s[2:3], s[4:5], exec
	s_cselect_b32 s29, s21, s23
	s_cselect_b32 s28, s20, s22
	s_lshl_b64 s[2:3], s[16:17], 21
	s_add_u32 s17, s36, s2
	ds_read_b128 v[2:5], v142
	ds_read_b128 v[6:9], v142 offset:1024
	ds_read_b128 v[10:13], v142 offset:2048
	ds_read_b128 v[14:17], v142 offset:3072
	ds_read_b128 v[18:21], v143
	ds_read_b128 v[22:25], v143 offset:1024
	ds_read_b128 v[26:29], v143 offset:2048
	ds_read_b128 v[30:33], v143 offset:3072
	s_addc_u32 s26, s37, s3
	s_ashr_i32 s15, s14, 31
	s_lshl_b64 s[2:3], s[14:15], 17
	s_add_u32 s2, s17, s2
	s_addc_u32 s3, s26, s3
	s_and_b64 s[26:27], s[4:5], exec
	s_cselect_b32 s27, s3, s25
	s_cselect_b32 s26, s2, s24
	s_add_u32 s34, s22, 0x1000
	s_addc_u32 s35, s23, 0
	s_add_u32 s54, s24, 0x1000
	s_addc_u32 s55, s25, 0
	s_add_u32 s30, s22, 0x1800
	s_addc_u32 s31, s23, 0
	s_add_u32 s56, s22, 0x10800
	s_addc_u32 s57, s23, 0
	s_mov_b32 m0, s50
	v_lshl_add_u64 v[66:67], s[56:57], 0, v[130:131]
	ds_read_b128 v[34:37], v144
	ds_read_b128 v[38:41], v144 offset:1024
	ds_read_b128 v[42:45], v144 offset:2048
	ds_read_b128 v[46:49], v144 offset:3072
	ds_read_b128 v[50:53], v144 offset:4096
	ds_read_b128 v[54:57], v144 offset:5120
	ds_read_b128 v[58:61], v144 offset:6144
	ds_read_b128 v[62:65], v144 offset:7168
	global_load_lds_dwordx4 v[66:67], off
	v_lshl_add_u64 v[66:67], s[56:57], 0, v[132:133]
	s_mov_b32 m0, s51
	s_nop 0
	global_load_lds_dwordx4 v[66:67], off
	s_waitcnt vmcnt(8)
	s_waitcnt lgkmcnt(0)
	s_barrier
	s_setprio 1
	v_mfma_f32_16x16x32_bf16 v[66:69], v[2:5], v[34:37], 0
	v_mfma_f32_16x16x32_bf16 v[70:73], v[10:13], v[34:37], 0
	v_mfma_f32_16x16x32_bf16 v[74:77], v[2:5], v[42:45], 0
	v_mfma_f32_16x16x32_bf16 v[78:81], v[10:13], v[42:45], 0
	v_mfma_f32_16x16x32_bf16 v[82:85], v[2:5], v[50:53], 0
	v_mfma_f32_16x16x32_bf16 v[86:89], v[10:13], v[50:53], 0
	v_mfma_f32_16x16x32_bf16 v[90:93], v[2:5], v[58:61], 0
	v_mfma_f32_16x16x32_bf16 v[94:97], v[10:13], v[58:61], 0
	v_mfma_f32_16x16x32_bf16 v[66:69], v[6:9], v[38:41], v[66:69]
	v_mfma_f32_16x16x32_bf16 v[70:73], v[14:17], v[38:41], v[70:73]
	v_mfma_f32_16x16x32_bf16 v[74:77], v[6:9], v[46:49], v[74:77]
	v_mfma_f32_16x16x32_bf16 v[78:81], v[14:17], v[46:49], v[78:81]
	v_mfma_f32_16x16x32_bf16 v[82:85], v[6:9], v[54:57], v[82:85]
	v_mfma_f32_16x16x32_bf16 v[86:89], v[14:17], v[54:57], v[86:89]
	v_mfma_f32_16x16x32_bf16 v[90:93], v[6:9], v[62:65], v[90:93]
	v_mfma_f32_16x16x32_bf16 v[94:97], v[14:17], v[62:65], v[94:97]
	s_setprio 0
	s_setprio 1
	v_mfma_f32_16x16x32_bf16 v[98:101], v[18:21], v[34:37], 0
	v_mfma_f32_16x16x32_bf16 v[34:37], v[26:29], v[34:37], 0
	v_mfma_f32_16x16x32_bf16 v[98:101], v[22:25], v[38:41], v[98:101]
	v_mfma_f32_16x16x32_bf16 v[34:37], v[30:33], v[38:41], v[34:37]
	v_mfma_f32_16x16x32_bf16 v[38:41], v[18:21], v[42:45], 0
	v_mfma_f32_16x16x32_bf16 v[42:45], v[26:29], v[42:45], 0
	v_mfma_f32_16x16x32_bf16 v[38:41], v[22:25], v[46:49], v[38:41]
	v_mfma_f32_16x16x32_bf16 v[42:45], v[30:33], v[46:49], v[42:45]
	v_mfma_f32_16x16x32_bf16 v[46:49], v[18:21], v[50:53], 0
	v_mfma_f32_16x16x32_bf16 v[50:53], v[26:29], v[50:53], 0
	v_mfma_f32_16x16x32_bf16 v[46:49], v[22:25], v[54:57], v[46:49]
	v_mfma_f32_16x16x32_bf16 v[50:53], v[30:33], v[54:57], v[50:53]
	v_mfma_f32_16x16x32_bf16 v[54:57], v[18:21], v[58:61], 0
	v_mfma_f32_16x16x32_bf16 v[58:61], v[26:29], v[58:61], 0
	v_mfma_f32_16x16x32_bf16 v[54:57], v[22:25], v[62:65], v[54:57]
	v_mfma_f32_16x16x32_bf16 v[58:61], v[30:33], v[62:65], v[58:61]
	s_setprio 0
	s_barrier
	s_mov_b32 m0, s52
	v_lshl_add_u64 v[146:147], s[54:55], 0, v[130:131]
	s_add_i32 s15, s52, 0x2000
	ds_read_b128 v[62:65], v144 offset:16384
	ds_read_b128 v[102:105], v144 offset:17408
	ds_read_b128 v[106:109], v144 offset:18432
	ds_read_b128 v[110:113], v144 offset:19456
	ds_read_b128 v[114:117], v144 offset:20480
	ds_read_b128 v[118:121], v144 offset:21504
	ds_read_b128 v[122:125], v144 offset:22528
	ds_read_b128 v[126:129], v144 offset:23552
	global_load_lds_dwordx4 v[146:147], off
	v_lshl_add_u64 v[146:147], s[54:55], 0, v[132:133]
	s_add_u32 s54, s24, 0x11000
	s_mov_b32 m0, s15
	s_addc_u32 s55, s25, 0
	s_add_i32 s17, s48, s38
	global_load_lds_dwordx4 v[146:147], off
	v_lshl_add_u64 v[146:147], s[54:55], 0, v[130:131]
	s_mov_b32 m0, s17
	s_nop 0
	global_load_lds_dwordx4 v[146:147], off
	v_lshl_add_u64 v[146:147], s[54:55], 0, v[132:133]
	s_add_i32 s54, s17, 0x2000
	s_mov_b32 m0, s54
	s_nop 0
	global_load_lds_dwordx4 v[146:147], off
	v_lshl_add_u64 v[146:147], s[34:35], 0, v[130:131]
	s_mov_b32 m0, s19
	s_nop 0
	global_load_lds_dwordx4 v[146:147], off
	v_lshl_add_u64 v[146:147], s[34:35], 0, v[132:133]
	s_mov_b32 m0, s39
	s_nop 0
	global_load_lds_dwordx4 v[146:147], off
	s_waitcnt vmcnt(8)
	s_waitcnt lgkmcnt(0)
	s_barrier
; #define PG8_STAGE(bufoff, gbase, voff) do { _Pragma("unroll") for (int _i = 0; _i < 2; ++_i) \
;         __builtin_amdgcn_global_load_lds((const unsigned*)((const char*)(gbase) + (voff)[_i]), (PG8_LAS unsigned*)(lds + (bufoff) + ldsw + _i * 8192), 16, 0, 0); } while (0)
; #define PG8_LDA(dst, b, h) do { _Pragma("unroll") for (int m = 0; m < 4; ++m) _Pragma("unroll") for (int k = 0; k < 2; ++k) dst[m][k] = *(const PG8_LAS bf16x8*)(lds + PG8_SA(b, h) + aoff + m * 2048 + k * 1024); } while (0)
; #define PG8_LDB(dst, b, h) do { _Pragma("unroll") for (int n = 0; n < 2; ++n) _Pragma("unroll") for (int k = 0; k < 2; ++k) dst[n][k] = *(const PG8_LAS bf16x8*)(lds + PG8_SB(b, h) + boff + n * 2048 + k * 1024); } while (0)
; #define PG8_MMA(ai, bj, At, Bt) do { __builtin_amdgcn_s_setprio(1); _Pragma("unroll") for (int m = 0; m < 4; ++m) _Pragma("unroll") for (int n = 0; n < 2; ++n) _Pragma("unroll") for (int k = 0; k < 2; ++k) \
;         acc[ai][bj][m][n] = __builtin_amdgcn_mfma_f32_16x16x32_bf16(Bt[n][k], At[m][k], acc[ai][bj][m][n], 0, 0, 0); __builtin_amdgcn_s_setprio(0); } while (0)
; #define PG8_BAR __builtin_amdgcn_s_barrier()
; template <class Epi, class Sched, bool ALIGN_EPI, int LMASK = -1, int LMASKB = LMASK>
; __device__ __forceinline__ void gemm_phase(PG8_LAS unsigned char* lds, const Gemm g, const Sched& S, const Epi& E) {
;     ...
;             PG8_LDB(B0, 0, 0); PG8_LDB(B1, 0, 1); PG8_SCHED; PG8_LDA(At, 0, 0); PG8_STAGE(PG8_SA(1, 1), a1 + hstepA, voffA);
;             PG8_WAIT_V(8); PG8_WAIT_L(0); PG8_BAR; PG8_MMA(0, 0, At, B0); PG8_MMA(0, 1, At, B1); PG8_BAR; PG8_SCHED;
;             PG8_LDA(At, 0, 1); PG8_STAGE(PG8_SB(0, 0), b2, voffB); PG8_STAGE(PG8_SB(0, 1), b2 + hstepB, voffB); PG8_STAGE(PG8_SA(0, 0), a2, voffA);
;             PG8_WAIT_V(8); PG8_WAIT_L(0); PG8_BAR; PG8_MMA(1, 0, At, B0); PG8_MMA(1, 1, At, B1); PG8_BAR; PG8_SCHED;
;             PG8_LDB(B0, 1, 0); PG8_LDB(B1, 1, 1); PG8_SCHED; PG8_LDA(At, 1, 0); PG8_STAGE(PG8_SA(0, 1), a2 + hstepA, voffA);
;             PG8_WAIT_V(8); PG8_WAIT_L(0); PG8_BAR; PG8_MMA(0, 0, At, B0); PG8_MMA(0, 1, At, B1); PG8_BAR; PG8_SCHED;
;             PG8_LDA(At, 1, 1); PG8_STAGE(PG8_SB(1, 0), b3, voffB); PG8_STAGE(PG8_SB(1, 1), b3 + hstepB, voffB); PG8_STAGE(PG8_SA(1, 0), a3, voffA);
;             PG8_WAIT_V(8); PG8_WAIT_L(0); PG8_BAR; PG8_MMA(1, 0, At, B0); PG8_MMA(1, 1, At, B1); PG8_BAR; PG8_SCHED;
	s_setprio 1
	v_mfma_f32_16x16x32_bf16 v[146:149], v[2:5], v[62:65], 0
	v_mfma_f32_16x16x32_bf16 v[154:157], v[2:5], v[106:109], 0
	v_mfma_f32_16x16x32_bf16 v[162:165], v[2:5], v[114:117], 0
	v_mfma_f32_16x16x32_bf16 v[2:5], v[2:5], v[122:125], 0
	v_mfma_f32_16x16x32_bf16 v[146:149], v[6:9], v[102:105], v[146:149]
	v_mfma_f32_16x16x32_bf16 v[154:157], v[6:9], v[110:113], v[154:157]
	v_mfma_f32_16x16x32_bf16 v[162:165], v[6:9], v[118:121], v[162:165]
	v_mfma_f32_16x16x32_bf16 v[2:5], v[6:9], v[126:129], v[2:5]
	v_mfma_f32_16x16x32_bf16 v[6:9], v[10:13], v[122:125], 0
	v_mfma_f32_16x16x32_bf16 v[150:153], v[10:13], v[62:65], 0
	v_mfma_f32_16x16x32_bf16 v[158:161], v[10:13], v[106:109], 0
	v_mfma_f32_16x16x32_bf16 v[166:169], v[10:13], v[114:117], 0
	v_mfma_f32_16x16x32_bf16 v[6:9], v[14:17], v[126:129], v[6:9]
	v_mfma_f32_16x16x32_bf16 v[150:153], v[14:17], v[102:105], v[150:153]
	v_mfma_f32_16x16x32_bf16 v[158:161], v[14:17], v[110:113], v[158:161]
	v_mfma_f32_16x16x32_bf16 v[166:169], v[14:17], v[118:121], v[166:169]
	s_setprio 0
	s_setprio 1
	v_mfma_f32_16x16x32_bf16 v[10:13], v[18:21], v[62:65], 0
	v_mfma_f32_16x16x32_bf16 v[14:17], v[26:29], v[62:65], 0
	v_mfma_f32_16x16x32_bf16 v[10:13], v[22:25], v[102:105], v[10:13]
	v_mfma_f32_16x16x32_bf16 v[14:17], v[30:33], v[102:105], v[14:17]
	v_mfma_f32_16x16x32_bf16 v[62:65], v[18:21], v[106:109], 0
	v_mfma_f32_16x16x32_bf16 v[102:105], v[26:29], v[106:109], 0
	v_mfma_f32_16x16x32_bf16 v[106:109], v[18:21], v[114:117], 0
	v_mfma_f32_16x16x32_bf16 v[18:21], v[18:21], v[122:125], 0
	v_mfma_f32_16x16x32_bf16 v[62:65], v[22:25], v[110:113], v[62:65]
	v_mfma_f32_16x16x32_bf16 v[102:105], v[30:33], v[110:113], v[102:105]
	v_mfma_f32_16x16x32_bf16 v[106:109], v[22:25], v[118:121], v[106:109]
	v_mfma_f32_16x16x32_bf16 v[110:113], v[26:29], v[114:117], 0
	v_mfma_f32_16x16x32_bf16 v[18:21], v[22:25], v[126:129], v[18:21]
	v_mfma_f32_16x16x32_bf16 v[22:25], v[26:29], v[122:125], 0
	v_mfma_f32_16x16x32_bf16 v[110:113], v[30:33], v[118:121], v[110:113]
	v_mfma_f32_16x16x32_bf16 v[22:25], v[30:33], v[126:129], v[22:25]
	s_setprio 0
	s_barrier
	s_add_i32 s55, 0, 0x18000
	s_add_i32 s58, 0, 0x1c000
	v_add_u32_e32 v134, s55, v1
	v_add_u32_e32 v222, s58, v1
	ds_read_b128 v[26:29], v134
	ds_read_b128 v[30:33], v134 offset:1024
	ds_read_b128 v[114:117], v134 offset:2048
	ds_read_b128 v[118:121], v134 offset:3072
	ds_read_b128 v[122:125], v222
	ds_read_b128 v[126:129], v222 offset:1024
	ds_read_b128 v[170:173], v222 offset:2048
	ds_read_b128 v[174:177], v222 offset:3072
	s_add_u32 s34, s22, 0x11000
	s_addc_u32 s35, s23, 0
	s_mov_b32 m0, s40
	v_lshl_add_u64 v[210:211], s[34:35], 0, v[130:131]
	ds_read_b128 v[178:181], v144 offset:32768
	ds_read_b128 v[182:185], v144 offset:33792
	ds_read_b128 v[186:189], v144 offset:34816
	ds_read_b128 v[190:193], v144 offset:35840
	ds_read_b128 v[194:197], v144 offset:36864
	ds_read_b128 v[198:201], v144 offset:37888
	ds_read_b128 v[202:205], v144 offset:38912
	ds_read_b128 v[206:209], v144 offset:39936
	global_load_lds_dwordx4 v[210:211], off
	v_lshl_add_u64 v[210:211], s[34:35], 0, v[132:133]
	s_mov_b32 m0, s41
	s_nop 0
	global_load_lds_dwordx4 v[210:211], off
	s_waitcnt vmcnt(8)
	s_waitcnt lgkmcnt(0)
	s_barrier
	s_setprio 1
	v_mfma_f32_16x16x32_bf16 v[66:69], v[26:29], v[178:181], v[66:69]
	v_mfma_f32_16x16x32_bf16 v[70:73], v[114:117], v[178:181], v[70:73]
	v_mfma_f32_16x16x32_bf16 v[74:77], v[26:29], v[186:189], v[74:77]
	v_mfma_f32_16x16x32_bf16 v[78:81], v[114:117], v[186:189], v[78:81]
	v_mfma_f32_16x16x32_bf16 v[82:85], v[26:29], v[194:197], v[82:85]
	v_mfma_f32_16x16x32_bf16 v[86:89], v[114:117], v[194:197], v[86:89]
	v_mfma_f32_16x16x32_bf16 v[90:93], v[26:29], v[202:205], v[90:93]
	v_mfma_f32_16x16x32_bf16 v[94:97], v[114:117], v[202:205], v[94:97]
	v_mfma_f32_16x16x32_bf16 v[66:69], v[30:33], v[182:185], v[66:69]
	v_mfma_f32_16x16x32_bf16 v[70:73], v[118:121], v[182:185], v[70:73]
	v_mfma_f32_16x16x32_bf16 v[74:77], v[30:33], v[190:193], v[74:77]
	v_mfma_f32_16x16x32_bf16 v[78:81], v[118:121], v[190:193], v[78:81]
	v_mfma_f32_16x16x32_bf16 v[82:85], v[30:33], v[198:201], v[82:85]
	v_mfma_f32_16x16x32_bf16 v[86:89], v[118:121], v[198:201], v[86:89]
	v_mfma_f32_16x16x32_bf16 v[90:93], v[30:33], v[206:209], v[90:93]
	v_mfma_f32_16x16x32_bf16 v[94:97], v[118:121], v[206:209], v[94:97]
	s_setprio 0
	s_setprio 1
	v_mfma_f32_16x16x32_bf16 v[98:101], v[122:125], v[178:181], v[98:101]
	v_mfma_f32_16x16x32_bf16 v[34:37], v[170:173], v[178:181], v[34:37]
	v_mfma_f32_16x16x32_bf16 v[38:41], v[122:125], v[186:189], v[38:41]
	v_mfma_f32_16x16x32_bf16 v[42:45], v[170:173], v[186:189], v[42:45]
	v_mfma_f32_16x16x32_bf16 v[46:49], v[122:125], v[194:197], v[46:49]
	v_mfma_f32_16x16x32_bf16 v[50:53], v[170:173], v[194:197], v[50:53]
	v_mfma_f32_16x16x32_bf16 v[54:57], v[122:125], v[202:205], v[54:57]
	v_mfma_f32_16x16x32_bf16 v[58:61], v[170:173], v[202:205], v[58:61]
	v_mfma_f32_16x16x32_bf16 v[98:101], v[126:129], v[182:185], v[98:101]
	v_mfma_f32_16x16x32_bf16 v[34:37], v[174:177], v[182:185], v[34:37]
	v_mfma_f32_16x16x32_bf16 v[38:41], v[126:129], v[190:193], v[38:41]
	v_mfma_f32_16x16x32_bf16 v[42:45], v[174:177], v[190:193], v[42:45]
	v_mfma_f32_16x16x32_bf16 v[46:49], v[126:129], v[198:201], v[46:49]
	v_mfma_f32_16x16x32_bf16 v[50:53], v[174:177], v[198:201], v[50:53]
	v_mfma_f32_16x16x32_bf16 v[54:57], v[126:129], v[206:209], v[54:57]
	v_mfma_f32_16x16x32_bf16 v[58:61], v[174:177], v[206:209], v[58:61]
	s_setprio 0
	s_barrier
; #define PG8_STAGE(bufoff, gbase, voff) do { _Pragma("unroll") for (int _i = 0; _i < 2; ++_i) \
;         __builtin_amdgcn_global_load_lds((const unsigned*)((const char*)(gbase) + (voff)[_i]), (PG8_LAS unsigned*)(lds + (bufoff) + ldsw + _i * 8192), 16, 0, 0); } while (0)
; #define PG8_LDA(dst, b, h) do { _Pragma("unroll") for (int m = 0; m < 4; ++m) _Pragma("unroll") for (int k = 0; k < 2; ++k) dst[m][k] = *(const PG8_LAS bf16x8*)(lds + PG8_SA(b, h) + aoff + m * 2048 + k * 1024); } while (0)
; #define PG8_LDB(dst, b, h) do { _Pragma("unroll") for (int n = 0; n < 2; ++n) _Pragma("unroll") for (int k = 0; k < 2; ++k) dst[n][k] = *(const PG8_LAS bf16x8*)(lds + PG8_SB(b, h) + boff + n * 2048 + k * 1024); } while (0)
; #define PG8_MMA(ai, bj, At, Bt) do { __builtin_amdgcn_s_setprio(1); _Pragma("unroll") for (int m = 0; m < 4; ++m) _Pragma("unroll") for (int n = 0; n < 2; ++n) _Pragma("unroll") for (int k = 0; k < 2; ++k) \
;         acc[ai][bj][m][n] = __builtin_amdgcn_mfma_f32_16x16x32_bf16(Bt[n][k], At[m][k], acc[ai][bj][m][n], 0, 0, 0); __builtin_amdgcn_s_setprio(0); } while (0)
; #define PG8_BAR __builtin_amdgcn_s_barrier()
; template <class Epi, class Sched, bool ALIGN_EPI, int LMASK = -1, int LMASKB = LMASK>
; __device__ __forceinline__ void gemm_phase(PG8_LAS unsigned char* lds, const Gemm g, const Sched& S, const Epi& E) {
;     ...
;             PG8_LDB(B0, 0, 0); PG8_LDB(B1, 0, 1); PG8_SCHED; PG8_LDA(At, 0, 0); PG8_STAGE(PG8_SA(1, 1), a1 + hstepA, voffA);
;             PG8_WAIT_V(8); PG8_WAIT_L(0); PG8_BAR; PG8_MMA(0, 0, At, B0); PG8_MMA(0, 1, At, B1); PG8_BAR; PG8_SCHED;
;             PG8_LDA(At, 0, 1); PG8_STAGE(PG8_SB(0, 0), b2, voffB); PG8_STAGE(PG8_SB(0, 1), b2 + hstepB, voffB); PG8_STAGE(PG8_SA(0, 0), a2, voffA);
;             PG8_WAIT_V(8); PG8_WAIT_L(0); PG8_BAR; PG8_MMA(1, 0, At, B0); PG8_MMA(1, 1, At, B1); PG8_BAR; PG8_SCHED;
;             PG8_LDB(B0, 1, 0); PG8_LDB(B1, 1, 1); PG8_SCHED; PG8_LDA(At, 1, 0); PG8_STAGE(PG8_SA(0, 1), a2 + hstepA, voffA);
;             PG8_WAIT_V(8); PG8_WAIT_L(0); PG8_BAR; PG8_MMA(0, 0, At, B0); PG8_MMA(0, 1, At, B1); PG8_BAR; PG8_SCHED;
;             PG8_LDA(At, 1, 1); PG8_STAGE(PG8_SB(1, 0), b3, voffB); PG8_STAGE(PG8_SB(1, 1), b3 + hstepB, voffB); PG8_STAGE(PG8_SA(1, 0), a3, voffA);
;             PG8_WAIT_V(8); PG8_WAIT_L(0); PG8_BAR; PG8_MMA(1, 0, At, B0); PG8_MMA(1, 1, At, B1); PG8_BAR; PG8_SCHED;
	s_add_u32 s56, s24, 0x1800
	s_addc_u32 s57, s25, 0
	s_add_i32 s35, s55, s38
	v_lshl_add_u64 v[210:211], s[56:57], 0, v[130:131]
	s_mov_b32 m0, s35
	s_add_i32 s34, s35, 0x2000
	ds_read_b128 v[178:181], v144 offset:49152
	ds_read_b128 v[182:185], v144 offset:50176
	ds_read_b128 v[186:189], v144 offset:51200
	ds_read_b128 v[190:193], v144 offset:52224
	ds_read_b128 v[194:197], v144 offset:53248
	ds_read_b128 v[198:201], v144 offset:54272
	ds_read_b128 v[202:205], v144 offset:55296
	ds_read_b128 v[206:209], v144 offset:56320
	global_load_lds_dwordx4 v[210:211], off
	v_lshl_add_u64 v[210:211], s[56:57], 0, v[132:133]
	s_add_u32 s56, s24, 0x11800
	s_mov_b32 m0, s34
	s_addc_u32 s57, s25, 0
	s_add_i32 s24, s58, s38
	global_load_lds_dwordx4 v[210:211], off
	v_lshl_add_u64 v[210:211], s[56:57], 0, v[130:131]
	s_mov_b32 m0, s24
	s_add_i32 s25, s24, 0x2000
	global_load_lds_dwordx4 v[210:211], off
	v_lshl_add_u64 v[210:211], s[56:57], 0, v[132:133]
	s_mov_b32 m0, s25
	s_nop 0
	global_load_lds_dwordx4 v[210:211], off
	v_lshl_add_u64 v[210:211], s[30:31], 0, v[130:131]
	s_mov_b32 m0, s44
	s_nop 0
	global_load_lds_dwordx4 v[210:211], off
	v_lshl_add_u64 v[210:211], s[30:31], 0, v[132:133]
	s_mov_b32 m0, s45
	s_nop 0
	global_load_lds_dwordx4 v[210:211], off
	s_waitcnt vmcnt(8)
	s_waitcnt lgkmcnt(0)
	s_barrier
	s_setprio 1
	v_mfma_f32_16x16x32_bf16 v[2:5], v[26:29], v[202:205], v[2:5]
	v_mfma_f32_16x16x32_bf16 v[6:9], v[114:117], v[202:205], v[6:9]
	v_mfma_f32_16x16x32_bf16 v[146:149], v[26:29], v[178:181], v[146:149]
	v_mfma_f32_16x16x32_bf16 v[150:153], v[114:117], v[178:181], v[150:153]
	v_mfma_f32_16x16x32_bf16 v[154:157], v[26:29], v[186:189], v[154:157]
	v_mfma_f32_16x16x32_bf16 v[158:161], v[114:117], v[186:189], v[158:161]
	v_mfma_f32_16x16x32_bf16 v[162:165], v[26:29], v[194:197], v[162:165]
	v_mfma_f32_16x16x32_bf16 v[166:169], v[114:117], v[194:197], v[166:169]
	v_mfma_f32_16x16x32_bf16 v[2:5], v[30:33], v[206:209], v[2:5]
	v_mfma_f32_16x16x32_bf16 v[6:9], v[118:121], v[206:209], v[6:9]
	v_mfma_f32_16x16x32_bf16 v[146:149], v[30:33], v[182:185], v[146:149]
	v_mfma_f32_16x16x32_bf16 v[150:153], v[118:121], v[182:185], v[150:153]
	v_mfma_f32_16x16x32_bf16 v[154:157], v[30:33], v[190:193], v[154:157]
	v_mfma_f32_16x16x32_bf16 v[158:161], v[118:121], v[190:193], v[158:161]
	v_mfma_f32_16x16x32_bf16 v[162:165], v[30:33], v[198:201], v[162:165]
	v_mfma_f32_16x16x32_bf16 v[166:169], v[118:121], v[198:201], v[166:169]
	s_setprio 0
	s_setprio 1
	v_mfma_f32_16x16x32_bf16 v[10:13], v[122:125], v[178:181], v[10:13]
	v_mfma_f32_16x16x32_bf16 v[14:17], v[170:173], v[178:181], v[14:17]
	v_mfma_f32_16x16x32_bf16 v[26:29], v[122:125], v[186:189], v[62:65]
	v_mfma_f32_16x16x32_bf16 v[30:33], v[170:173], v[186:189], v[102:105]
	v_mfma_f32_16x16x32_bf16 v[62:65], v[122:125], v[194:197], v[106:109]
	v_mfma_f32_16x16x32_bf16 v[102:105], v[170:173], v[194:197], v[110:113]
	v_mfma_f32_16x16x32_bf16 v[18:21], v[122:125], v[202:205], v[18:21]
	v_mfma_f32_16x16x32_bf16 v[22:25], v[170:173], v[202:205], v[22:25]
	v_mfma_f32_16x16x32_bf16 v[10:13], v[126:129], v[182:185], v[10:13]
	v_mfma_f32_16x16x32_bf16 v[14:17], v[174:177], v[182:185], v[14:17]
	v_mfma_f32_16x16x32_bf16 v[26:29], v[126:129], v[190:193], v[26:29]
	v_mfma_f32_16x16x32_bf16 v[30:33], v[174:177], v[190:193], v[30:33]
	v_mfma_f32_16x16x32_bf16 v[62:65], v[126:129], v[198:201], v[62:65]
	v_mfma_f32_16x16x32_bf16 v[102:105], v[174:177], v[198:201], v[102:105]
	v_mfma_f32_16x16x32_bf16 v[18:21], v[126:129], v[206:209], v[18:21]
	v_mfma_f32_16x16x32_bf16 v[22:25], v[174:177], v[206:209], v[22:25]
	s_setprio 0
	s_barrier
	ds_read_b128 v[106:109], v142
	ds_read_b128 v[110:113], v142 offset:1024
	ds_read_b128 v[114:117], v142 offset:2048
	ds_read_b128 v[118:121], v142 offset:3072
	ds_read_b128 v[122:125], v143
	ds_read_b128 v[126:129], v143 offset:1024
	ds_read_b128 v[170:173], v143 offset:2048
	ds_read_b128 v[174:177], v143 offset:3072
	s_add_u32 s22, s22, 0x11800
	s_addc_u32 s23, s23, 0
	s_mov_b32 m0, s50
	v_lshl_add_u64 v[210:211], s[22:23], 0, v[130:131]
	ds_read_b128 v[178:181], v144
	ds_read_b128 v[182:185], v144 offset:1024
	ds_read_b128 v[186:189], v144 offset:2048
	ds_read_b128 v[190:193], v144 offset:3072
	ds_read_b128 v[194:197], v144 offset:4096
	ds_read_b128 v[198:201], v144 offset:5120
	ds_read_b128 v[202:205], v144 offset:6144
	ds_read_b128 v[206:209], v144 offset:7168
	global_load_lds_dwordx4 v[210:211], off
	v_lshl_add_u64 v[210:211], s[22:23], 0, v[132:133]
	s_mov_b32 m0, s51
	s_nop 0
	global_load_lds_dwordx4 v[210:211], off
	s_waitcnt vmcnt(8)
	s_waitcnt lgkmcnt(0)
	s_barrier
; #define PG8_STAGE(bufoff, gbase, voff) do { _Pragma("unroll") for (int _i = 0; _i < 2; ++_i) \
;         __builtin_amdgcn_global_load_lds((const unsigned*)((const char*)(gbase) + (voff)[_i]), (PG8_LAS unsigned*)(lds + (bufoff) + ldsw + _i * 8192), 16, 0, 0); } while (0)
; #define PG8_LDA(dst, b, h) do { _Pragma("unroll") for (int m = 0; m < 4; ++m) _Pragma("unroll") for (int k = 0; k < 2; ++k) dst[m][k] = *(const PG8_LAS bf16x8*)(lds + PG8_SA(b, h) + aoff + m * 2048 + k * 1024); } while (0)
; #define PG8_LDB(dst, b, h) do { _Pragma("unroll") for (int n = 0; n < 2; ++n) _Pragma("unroll") for (int k = 0; k < 2; ++k) dst[n][k] = *(const PG8_LAS bf16x8*)(lds + PG8_SB(b, h) + boff + n * 2048 + k * 1024); } while (0)
; #define PG8_MMA(ai, bj, At, Bt) do { __builtin_amdgcn_s_setprio(1); _Pragma("unroll") for (int m = 0; m < 4; ++m) _Pragma("unroll") for (int n = 0; n < 2; ++n) _Pragma("unroll") for (int k = 0; k < 2; ++k) \
;         acc[ai][bj][m][n] = __builtin_amdgcn_mfma_f32_16x16x32_bf16(Bt[n][k], At[m][k], acc[ai][bj][m][n], 0, 0, 0); __builtin_amdgcn_s_setprio(0); } while (0)
; #define PG8_BAR __builtin_amdgcn_s_barrier()
; template <class Epi, class Sched, bool ALIGN_EPI, int LMASK = -1, int LMASKB = LMASK>
; __device__ __forceinline__ void gemm_phase(PG8_LAS unsigned char* lds, const Gemm g, const Sched& S, const Epi& E) {
;     ...
;             PG8_LDB(B0, 0, 0); PG8_LDB(B1, 0, 1); PG8_SCHED; PG8_LDA(At, 0, 0); PG8_STAGE(PG8_SA(1, 1), a1 + hstepA, voffA);
;             PG8_WAIT_V(8); PG8_WAIT_L(0); PG8_BAR; PG8_MMA(0, 0, At, B0); PG8_MMA(0, 1, At, B1); PG8_BAR; PG8_SCHED;
;             PG8_LDA(At, 0, 1); PG8_STAGE(PG8_SB(0, 0), b2, voffB); PG8_STAGE(PG8_SB(0, 1), b2 + hstepB, voffB); PG8_STAGE(PG8_SA(0, 0), a2, voffA);
;             PG8_WAIT_V(8); PG8_WAIT_L(0); PG8_BAR; PG8_MMA(1, 0, At, B0); PG8_MMA(1, 1, At, B1); PG8_BAR; PG8_SCHED;
;             PG8_LDB(B0, 1, 0); PG8_LDB(B1, 1, 1); PG8_SCHED; PG8_LDA(At, 1, 0); PG8_STAGE(PG8_SA(0, 1), a2 + hstepA, voffA);
;             PG8_WAIT_V(8); PG8_WAIT_L(0); PG8_BAR; PG8_MMA(0, 0, At, B0); PG8_MMA(0, 1, At, B1); PG8_BAR; PG8_SCHED;
;             PG8_LDA(At, 1, 1); PG8_STAGE(PG8_SB(1, 0), b3, voffB); PG8_STAGE(PG8_SB(1, 1), b3 + hstepB, voffB); PG8_STAGE(PG8_SA(1, 0), a3, voffA);
;             PG8_WAIT_V(8); PG8_WAIT_L(0); PG8_BAR; PG8_MMA(1, 0, At, B0); PG8_MMA(1, 1, At, B1); PG8_BAR; PG8_SCHED;
	s_setprio 1
	v_mfma_f32_16x16x32_bf16 v[66:69], v[106:109], v[178:181], v[66:69]
	v_mfma_f32_16x16x32_bf16 v[70:73], v[114:117], v[178:181], v[70:73]
	v_mfma_f32_16x16x32_bf16 v[74:77], v[106:109], v[186:189], v[74:77]
	v_mfma_f32_16x16x32_bf16 v[78:81], v[114:117], v[186:189], v[78:81]
	v_mfma_f32_16x16x32_bf16 v[82:85], v[106:109], v[194:197], v[82:85]
	v_mfma_f32_16x16x32_bf16 v[86:89], v[114:117], v[194:197], v[86:89]
	v_mfma_f32_16x16x32_bf16 v[90:93], v[106:109], v[202:205], v[90:93]
	v_mfma_f32_16x16x32_bf16 v[94:97], v[114:117], v[202:205], v[94:97]
	v_mfma_f32_16x16x32_bf16 v[66:69], v[110:113], v[182:185], v[66:69]
	v_mfma_f32_16x16x32_bf16 v[70:73], v[118:121], v[182:185], v[70:73]
	v_mfma_f32_16x16x32_bf16 v[74:77], v[110:113], v[190:193], v[74:77]
	v_mfma_f32_16x16x32_bf16 v[78:81], v[118:121], v[190:193], v[78:81]
	v_mfma_f32_16x16x32_bf16 v[82:85], v[110:113], v[198:201], v[82:85]
	v_mfma_f32_16x16x32_bf16 v[86:89], v[118:121], v[198:201], v[86:89]
	v_mfma_f32_16x16x32_bf16 v[90:93], v[110:113], v[206:209], v[90:93]
	v_mfma_f32_16x16x32_bf16 v[94:97], v[118:121], v[206:209], v[94:97]
	s_setprio 0
	s_setprio 1
	v_mfma_f32_16x16x32_bf16 v[34:37], v[170:173], v[178:181], v[34:37]
	v_mfma_f32_16x16x32_bf16 v[98:101], v[122:125], v[178:181], v[98:101]
	v_mfma_f32_16x16x32_bf16 v[178:181], v[174:177], v[182:185], v[34:37]
	v_mfma_f32_16x16x32_bf16 v[34:37], v[122:125], v[186:189], v[38:41]
	v_mfma_f32_16x16x32_bf16 v[210:213], v[126:129], v[182:185], v[98:101]
	v_mfma_f32_16x16x32_bf16 v[182:185], v[126:129], v[190:193], v[34:37]
	v_mfma_f32_16x16x32_bf16 v[34:37], v[170:173], v[186:189], v[42:45]
	v_mfma_f32_16x16x32_bf16 v[42:45], v[174:177], v[190:193], v[34:37]
	v_mfma_f32_16x16x32_bf16 v[34:37], v[122:125], v[194:197], v[46:49]
	v_mfma_f32_16x16x32_bf16 v[46:49], v[126:129], v[198:201], v[34:37]
	v_mfma_f32_16x16x32_bf16 v[34:37], v[170:173], v[194:197], v[50:53]
	v_mfma_f32_16x16x32_bf16 v[50:53], v[174:177], v[198:201], v[34:37]
	v_mfma_f32_16x16x32_bf16 v[34:37], v[122:125], v[202:205], v[54:57]
	v_mfma_f32_16x16x32_bf16 v[54:57], v[126:129], v[206:209], v[34:37]
	v_mfma_f32_16x16x32_bf16 v[34:37], v[170:173], v[202:205], v[58:61]
	v_mfma_f32_16x16x32_bf16 v[58:61], v[174:177], v[206:209], v[34:37]
	s_setprio 0
	s_barrier
	s_mov_b32 m0, s52
	v_lshl_add_u64 v[246:247], s[26:27], 0, v[130:131]
	s_add_u32 s22, s26, 0x10000
	s_nop 1
	ds_read_b128 v[34:37], v144 offset:16384
	ds_read_b128 v[38:41], v144 offset:17408
	ds_read_b128 v[98:101], v144 offset:18432
	ds_read_b128 v[186:189], v144 offset:19456
	ds_read_b128 v[190:193], v144 offset:20480
	ds_read_b128 v[194:197], v144 offset:21504
	ds_read_b128 v[198:201], v144 offset:22528
	ds_read_b128 v[202:205], v144 offset:23552
	global_load_lds_dwordx4 v[246:247], off
	v_lshl_add_u64 v[248:249], s[26:27], 0, v[132:133]
	s_mov_b32 m0, s15
	s_addc_u32 s23, s27, 0
	global_load_lds_dwordx4 v[248:249], off
	v_lshl_add_u64 v[206:207], s[22:23], 0, v[130:131]
	s_mov_b32 m0, s17
	v_lshl_add_u64 v[250:251], s[28:29], 0, v[130:131]
	global_load_lds_dwordx4 v[206:207], off
	v_lshl_add_u64 v[206:207], s[22:23], 0, v[132:133]
	s_mov_b32 m0, s54
	v_lshl_add_u64 v[252:253], s[28:29], 0, v[132:133]
	global_load_lds_dwordx4 v[206:207], off
	s_mov_b32 m0, s19
	s_nop 0
	global_load_lds_dwordx4 v[250:251], off
	s_mov_b32 m0, s39
	s_nop 0
	global_load_lds_dwordx4 v[252:253], off
	s_waitcnt vmcnt(8)
	s_waitcnt lgkmcnt(0)
	s_barrier
	s_setprio 1
	v_mfma_f32_16x16x32_bf16 v[2:5], v[106:109], v[198:201], v[2:5]
	v_mfma_f32_16x16x32_bf16 v[6:9], v[114:117], v[198:201], v[6:9]
	v_mfma_f32_16x16x32_bf16 v[146:149], v[106:109], v[34:37], v[146:149]
	v_mfma_f32_16x16x32_bf16 v[150:153], v[114:117], v[34:37], v[150:153]
	v_mfma_f32_16x16x32_bf16 v[154:157], v[106:109], v[98:101], v[154:157]
	v_mfma_f32_16x16x32_bf16 v[158:161], v[114:117], v[98:101], v[158:161]
	v_mfma_f32_16x16x32_bf16 v[162:165], v[106:109], v[190:193], v[162:165]
	v_mfma_f32_16x16x32_bf16 v[166:169], v[114:117], v[190:193], v[166:169]
	v_mfma_f32_16x16x32_bf16 v[2:5], v[110:113], v[202:205], v[2:5]
	v_mfma_f32_16x16x32_bf16 v[6:9], v[118:121], v[202:205], v[6:9]
	v_mfma_f32_16x16x32_bf16 v[146:149], v[110:113], v[38:41], v[146:149]
	v_mfma_f32_16x16x32_bf16 v[150:153], v[118:121], v[38:41], v[150:153]
	v_mfma_f32_16x16x32_bf16 v[154:157], v[110:113], v[186:189], v[154:157]
	v_mfma_f32_16x16x32_bf16 v[158:161], v[118:121], v[186:189], v[158:161]
	v_mfma_f32_16x16x32_bf16 v[162:165], v[110:113], v[194:197], v[162:165]
	v_mfma_f32_16x16x32_bf16 v[166:169], v[118:121], v[194:197], v[166:169]
	s_setprio 0
	s_setprio 1
	v_mfma_f32_16x16x32_bf16 v[10:13], v[122:125], v[34:37], v[10:13]
	v_mfma_f32_16x16x32_bf16 v[14:17], v[170:173], v[34:37], v[14:17]
	v_mfma_f32_16x16x32_bf16 v[26:29], v[122:125], v[98:101], v[26:29]
	v_mfma_f32_16x16x32_bf16 v[30:33], v[170:173], v[98:101], v[30:33]
	v_mfma_f32_16x16x32_bf16 v[34:37], v[122:125], v[190:193], v[62:65]
	v_mfma_f32_16x16x32_bf16 v[26:29], v[126:129], v[186:189], v[26:29]
	v_mfma_f32_16x16x32_bf16 v[30:33], v[174:177], v[186:189], v[30:33]
	v_mfma_f32_16x16x32_bf16 v[186:189], v[126:129], v[194:197], v[34:37]
	v_mfma_f32_16x16x32_bf16 v[34:37], v[170:173], v[190:193], v[102:105]
	v_mfma_f32_16x16x32_bf16 v[18:21], v[122:125], v[198:201], v[18:21]
	v_mfma_f32_16x16x32_bf16 v[10:13], v[126:129], v[38:41], v[10:13]
	v_mfma_f32_16x16x32_bf16 v[14:17], v[174:177], v[38:41], v[14:17]
	v_mfma_f32_16x16x32_bf16 v[190:193], v[174:177], v[194:197], v[34:37]
	v_mfma_f32_16x16x32_bf16 v[194:197], v[126:129], v[202:205], v[18:21]
	v_mfma_f32_16x16x32_bf16 v[18:21], v[170:173], v[198:201], v[22:25]
	v_mfma_f32_16x16x32_bf16 v[170:173], v[174:177], v[202:205], v[18:21]
	s_setprio 0
	s_barrier
; #define PG8_STAGE(bufoff, gbase, voff) do { _Pragma("unroll") for (int _i = 0; _i < 2; ++_i) \
;         __builtin_amdgcn_global_load_lds((const unsigned*)((const char*)(gbase) + (voff)[_i]), (PG8_LAS unsigned*)(lds + (bufoff) + ldsw + _i * 8192), 16, 0, 0); } while (0)
; #define PG8_LDA(dst, b, h) do { _Pragma("unroll") for (int m = 0; m < 4; ++m) _Pragma("unroll") for (int k = 0; k < 2; ++k) dst[m][k] = *(const PG8_LAS bf16x8*)(lds + PG8_SA(b, h) + aoff + m * 2048 + k * 1024); } while (0)
; #define PG8_LDB(dst, b, h) do { _Pragma("unroll") for (int n = 0; n < 2; ++n) _Pragma("unroll") for (int k = 0; k < 2; ++k) dst[n][k] = *(const PG8_LAS bf16x8*)(lds + PG8_SB(b, h) + boff + n * 2048 + k * 1024); } while (0)
; #define PG8_MMA(ai, bj, At, Bt) do { __builtin_amdgcn_s_setprio(1); _Pragma("unroll") for (int m = 0; m < 4; ++m) _Pragma("unroll") for (int n = 0; n < 2; ++n) _Pragma("unroll") for (int k = 0; k < 2; ++k) \
;         acc[ai][bj][m][n] = __builtin_amdgcn_mfma_f32_16x16x32_bf16(Bt[n][k], At[m][k], acc[ai][bj][m][n], 0, 0, 0); __builtin_amdgcn_s_setprio(0); } while (0)
; #define PG8_WAIT_V(n) asm volatile("s_waitcnt vmcnt(" #n ")" ::: "memory")
; #define PG8_WAIT_L(n) asm volatile("s_waitcnt lgkmcnt(" #n ")" ::: "memory")
; #define PG8_BAR __builtin_amdgcn_s_barrier()
; #define PG8_SCHED __builtin_amdgcn_sched_barrier(0)
; template <class Epi, class Sched, bool ALIGN_EPI, int LMASK = -1, int LMASKB = LMASK>
; __device__ __forceinline__ void gemm_phase(PG8_LAS unsigned char* lds, const Gemm g, const Sched& S, const Epi& E) {
;     ...
;             PG8_LDB(B0, 1, 0); PG8_LDB(B1, 1, 1); PG8_SCHED; PG8_LDA(At, 1, 0); PG8_STAGE(PG8_SA(0, 1), a2 + hstepA, voffA);
;             PG8_WAIT_V(8); PG8_WAIT_L(0); PG8_BAR; PG8_MMA(0, 0, At, B0); PG8_MMA(0, 1, At, B1); PG8_BAR; PG8_SCHED;
;             PG8_LDA(At, 1, 1); PG8_STAGE(PG8_SB(1, 0), b3, voffB); PG8_STAGE(PG8_SB(1, 1), b3 + hstepB, voffB); PG8_STAGE(PG8_SA(1, 0), a3, voffA);
;             PG8_WAIT_V(8); PG8_WAIT_L(0); PG8_BAR; PG8_MMA(1, 0, At, B0); PG8_MMA(1, 1, At, B1); PG8_BAR; PG8_SCHED;
;         }
;         if constexpr (ALIGN_EPI) { if (wr == 0) PG8_BAR; }
;         E(acc, cur, wr, wc, fr, fq);
;         if (!has_next) break;
	ds_read_b128 v[62:65], v134
	ds_read_b128 v[174:177], v134 offset:1024
	ds_read_b128 v[198:201], v134 offset:2048
	ds_read_b128 v[202:205], v134 offset:3072
	ds_read_b128 v[206:209], v222
	ds_read_b128 v[214:217], v222 offset:1024
	ds_read_b128 v[218:221], v222 offset:2048
	ds_read_b128 v[222:225], v222 offset:3072
	s_add_u32 s22, s28, 0x10000
	s_addc_u32 s23, s29, 0
	s_mov_b32 m0, s40
	v_lshl_add_u64 v[34:35], s[22:23], 0, v[130:131]
	ds_read_b128 v[18:21], v144 offset:32768
	ds_read_b128 v[22:25], v144 offset:33792
	ds_read_b128 v[110:113], v144 offset:34816
	ds_read_b128 v[226:229], v144 offset:35840
	ds_read_b128 v[230:233], v144 offset:36864
	ds_read_b128 v[234:237], v144 offset:37888
	ds_read_b128 v[238:241], v144 offset:38912
	ds_read_b128 v[242:245], v144 offset:39936
	global_load_lds_dwordx4 v[34:35], off
	v_lshl_add_u64 v[34:35], s[22:23], 0, v[132:133]
	s_mov_b32 m0, s41
	s_nop 0
	global_load_lds_dwordx4 v[34:35], off
	s_waitcnt vmcnt(8)
	s_waitcnt lgkmcnt(0)
	s_barrier
	s_setprio 1
	v_mfma_f32_16x16x32_bf16 v[34:37], v[62:65], v[18:21], v[66:69]
	v_mfma_f32_16x16x32_bf16 v[114:117], v[174:177], v[22:25], v[34:37]
	v_mfma_f32_16x16x32_bf16 v[34:37], v[198:201], v[18:21], v[70:73]
	v_mfma_f32_16x16x32_bf16 v[118:121], v[202:205], v[22:25], v[34:37]
	v_mfma_f32_16x16x32_bf16 v[34:37], v[62:65], v[110:113], v[74:77]
	v_mfma_f32_16x16x32_bf16 v[98:101], v[174:177], v[226:229], v[34:37]
	v_mfma_f32_16x16x32_bf16 v[34:37], v[198:201], v[110:113], v[78:81]
	v_mfma_f32_16x16x32_bf16 v[102:105], v[202:205], v[226:229], v[34:37]
	v_mfma_f32_16x16x32_bf16 v[34:37], v[62:65], v[230:233], v[82:85]
	v_mfma_f32_16x16x32_bf16 v[66:69], v[174:177], v[234:237], v[34:37]
	v_mfma_f32_16x16x32_bf16 v[34:37], v[198:201], v[230:233], v[86:89]
	v_mfma_f32_16x16x32_bf16 v[70:73], v[202:205], v[234:237], v[34:37]
	v_mfma_f32_16x16x32_bf16 v[34:37], v[62:65], v[238:241], v[90:93]
	v_mfma_f32_16x16x32_bf16 v[38:41], v[198:201], v[238:241], v[94:97]
	v_mfma_f32_16x16x32_bf16 v[34:37], v[174:177], v[242:245], v[34:37]
	v_mfma_f32_16x16x32_bf16 v[38:41], v[202:205], v[242:245], v[38:41]
	s_setprio 0
	s_setprio 1
	v_mfma_f32_16x16x32_bf16 v[74:77], v[206:209], v[18:21], v[210:213]
	v_mfma_f32_16x16x32_bf16 v[18:21], v[218:221], v[18:21], v[178:181]
	v_mfma_f32_16x16x32_bf16 v[126:129], v[222:225], v[22:25], v[18:21]
	v_mfma_f32_16x16x32_bf16 v[18:21], v[206:209], v[110:113], v[182:185]
	v_mfma_f32_16x16x32_bf16 v[106:109], v[214:217], v[226:229], v[18:21]
	v_mfma_f32_16x16x32_bf16 v[18:21], v[218:221], v[110:113], v[42:45]
	v_mfma_f32_16x16x32_bf16 v[110:113], v[222:225], v[226:229], v[18:21]
	v_mfma_f32_16x16x32_bf16 v[18:21], v[206:209], v[230:233], v[46:49]
	v_mfma_f32_16x16x32_bf16 v[122:125], v[214:217], v[22:25], v[74:77]
	v_mfma_f32_16x16x32_bf16 v[74:77], v[214:217], v[234:237], v[18:21]
	v_mfma_f32_16x16x32_bf16 v[18:21], v[218:221], v[230:233], v[50:53]
	v_mfma_f32_16x16x32_bf16 v[78:81], v[222:225], v[234:237], v[18:21]
	v_mfma_f32_16x16x32_bf16 v[18:21], v[206:209], v[238:241], v[54:57]
	v_mfma_f32_16x16x32_bf16 v[42:45], v[214:217], v[242:245], v[18:21]
	v_mfma_f32_16x16x32_bf16 v[18:21], v[218:221], v[238:241], v[58:61]
	v_mfma_f32_16x16x32_bf16 v[46:49], v[222:225], v[242:245], v[18:21]
	s_setprio 0
	s_barrier
	s_mov_b32 m0, s35
	s_nop 3
	v_lshl_add_u64 v[18:19], v[246:247], 0, s[8:9]
	s_add_u32 s22, s26, 0x10800
	ds_read_b128 v[58:61], v144 offset:49152
	ds_read_b128 v[94:97], v144 offset:50176
	ds_read_b128 v[178:181], v144 offset:51200
	ds_read_b128 v[182:185], v144 offset:52224
	ds_read_b128 v[210:213], v144 offset:53248
	ds_read_b128 v[226:229], v144 offset:54272
	ds_read_b128 v[230:233], v144 offset:55296
	ds_read_b128 v[234:237], v144 offset:56320
	global_load_lds_dwordx4 v[18:19], off
	v_lshl_add_u64 v[18:19], v[248:249], 0, s[8:9]
	s_mov_b32 m0, s34
	s_addc_u32 s23, s27, 0
	global_load_lds_dwordx4 v[18:19], off
	v_lshl_add_u64 v[18:19], s[22:23], 0, v[130:131]
	s_mov_b32 m0, s24
	s_nop 0
	global_load_lds_dwordx4 v[18:19], off
	v_lshl_add_u64 v[18:19], s[22:23], 0, v[132:133]
	s_mov_b32 m0, s25
	s_nop 0
	global_load_lds_dwordx4 v[18:19], off
	v_lshl_add_u64 v[18:19], v[250:251], 0, s[8:9]
	s_mov_b32 m0, s44
	s_nop 0
	global_load_lds_dwordx4 v[18:19], off
	v_lshl_add_u64 v[18:19], v[252:253], 0, s[8:9]
	s_mov_b32 m0, s45
	s_nop 0
	global_load_lds_dwordx4 v[18:19], off
	s_waitcnt vmcnt(8)
	s_waitcnt lgkmcnt(0)
	s_barrier
	s_setprio 1
	v_mfma_f32_16x16x32_bf16 v[18:21], v[62:65], v[58:61], v[146:149]
	v_mfma_f32_16x16x32_bf16 v[82:85], v[174:177], v[94:97], v[18:21]
	v_mfma_f32_16x16x32_bf16 v[18:21], v[198:201], v[58:61], v[150:153]
	v_mfma_f32_16x16x32_bf16 v[86:89], v[202:205], v[94:97], v[18:21]
	v_mfma_f32_16x16x32_bf16 v[18:21], v[62:65], v[178:181], v[154:157]
	v_mfma_f32_16x16x32_bf16 v[50:53], v[174:177], v[182:185], v[18:21]
	v_mfma_f32_16x16x32_bf16 v[18:21], v[198:201], v[178:181], v[158:161]
	v_mfma_f32_16x16x32_bf16 v[54:57], v[202:205], v[182:185], v[18:21]
	v_mfma_f32_16x16x32_bf16 v[18:21], v[62:65], v[210:213], v[162:165]
	v_mfma_f32_16x16x32_bf16 v[22:25], v[198:201], v[210:213], v[166:169]
	v_mfma_f32_16x16x32_bf16 v[2:5], v[62:65], v[230:233], v[2:5]
	v_mfma_f32_16x16x32_bf16 v[6:9], v[198:201], v[230:233], v[6:9]
	v_mfma_f32_16x16x32_bf16 v[18:21], v[174:177], v[226:229], v[18:21]
	v_mfma_f32_16x16x32_bf16 v[22:25], v[202:205], v[226:229], v[22:25]
	v_mfma_f32_16x16x32_bf16 v[2:5], v[174:177], v[234:237], v[2:5]
	v_mfma_f32_16x16x32_bf16 v[6:9], v[202:205], v[234:237], v[6:9]
	s_setprio 0
	s_setprio 1
	v_mfma_f32_16x16x32_bf16 v[10:13], v[206:209], v[58:61], v[10:13]
	v_mfma_f32_16x16x32_bf16 v[90:93], v[214:217], v[94:97], v[10:13]
	v_mfma_f32_16x16x32_bf16 v[10:13], v[218:221], v[58:61], v[14:17]
	v_mfma_f32_16x16x32_bf16 v[94:97], v[222:225], v[94:97], v[10:13]
	v_mfma_f32_16x16x32_bf16 v[10:13], v[206:209], v[178:181], v[26:29]
	v_mfma_f32_16x16x32_bf16 v[58:61], v[214:217], v[182:185], v[10:13]
	v_mfma_f32_16x16x32_bf16 v[10:13], v[218:221], v[178:181], v[30:33]
	v_mfma_f32_16x16x32_bf16 v[62:65], v[222:225], v[182:185], v[10:13]
	v_mfma_f32_16x16x32_bf16 v[10:13], v[206:209], v[210:213], v[186:189]
	v_mfma_f32_16x16x32_bf16 v[26:29], v[214:217], v[226:229], v[10:13]
	v_mfma_f32_16x16x32_bf16 v[10:13], v[218:221], v[210:213], v[190:193]
	v_mfma_f32_16x16x32_bf16 v[30:33], v[222:225], v[226:229], v[10:13]
	v_mfma_f32_16x16x32_bf16 v[10:13], v[206:209], v[230:233], v[194:197]
	v_mfma_f32_16x16x32_bf16 v[14:17], v[218:221], v[230:233], v[170:173]
	v_mfma_f32_16x16x32_bf16 v[10:13], v[214:217], v[234:237], v[10:13]
	v_mfma_f32_16x16x32_bf16 v[14:17], v[222:225], v[234:237], v[14:17]
	s_setprio 0
	s_barrier
	s_andn2_b64 vcc, exec, s[10:11]
	s_cbranch_vccnz .LBB0_208
	s_barrier

; #define PG8_STAGE(bufoff, gbase, voff) do { _Pragma("unroll") for (int _i = 0; _i < 2; ++_i) \
;         __builtin_amdgcn_global_load_lds((const unsigned*)((const char*)(gbase) + (voff)[_i]), (PG8_LAS unsigned*)(lds + (bufoff) + ldsw + _i * 8192), 16, 0, 0); } while (0)
; #define PG8_LDA(dst, b, h) do { _Pragma("unroll") for (int m = 0; m < 4; ++m) _Pragma("unroll") for (int k = 0; k < 2; ++k) dst[m][k] = *(const PG8_LAS bf16x8*)(lds + PG8_SA(b, h) + aoff + m * 2048 + k * 1024); } while (0)
; #define PG8_LDB(dst, b, h) do { _Pragma("unroll") for (int n = 0; n < 2; ++n) _Pragma("unroll") for (int k = 0; k < 2; ++k) dst[n][k] = *(const PG8_LAS bf16x8*)(lds + PG8_SB(b, h) + boff + n * 2048 + k * 1024); } while (0)
; #define PG8_MMA(ai, bj, At, Bt) do { __builtin_amdgcn_s_setprio(1); _Pragma("unroll") for (int m = 0; m < 4; ++m) _Pragma("unroll") for (int n = 0; n < 2; ++n) _Pragma("unroll") for (int k = 0; k < 2; ++k) \
;         acc[ai][bj][m][n] = __builtin_amdgcn_mfma_f32_16x16x32_bf16(Bt[n][k], At[m][k], acc[ai][bj][m][n], 0, 0, 0); __builtin_amdgcn_s_setprio(0); } while (0)
; #define PG8_WAIT_V(n) asm volatile("s_waitcnt vmcnt(" #n ")" ::: "memory")
; #define PG8_WAIT_L(n) asm volatile("s_waitcnt lgkmcnt(" #n ")" ::: "memory")
; #define PG8_BAR __builtin_amdgcn_s_barrier()
; #define PG8_SCHED __builtin_amdgcn_sched_barrier(0)
; template <class Epi, class Sched, bool ALIGN_EPI, int LMASK = -1, int LMASKB = LMASK>
; __device__ __forceinline__ void gemm_phase(PG8_LAS unsigned char* lds, const Gemm g, const Sched& S, const Epi& E) {
;     ...
;             const bool last = (t == nt - 2);
;             const char* a1 = cA + (size_t)(t + 1) * kstepA;
;             const char* a2 = last ? nA : cA + (size_t)(t + 2) * kstepA; const char* b2 = last ? nB : cB + (size_t)(t + 2) * kstepB;
;             const char* a3 = a2 + kstepA; const char* b3 = b2 + kstepB;
;             PG8_LDB(B0, 0, 0); PG8_LDB(B1, 0, 1); PG8_SCHED; PG8_LDA(At, 0, 0); PG8_STAGE(PG8_SA(1, 1), a1 + hstepA, voffA);
;             PG8_WAIT_V(8); PG8_WAIT_L(0); PG8_BAR; PG8_MMA(0, 0, At, B0); PG8_MMA(0, 1, At, B1); PG8_BAR; PG8_SCHED;
;             PG8_LDA(At, 0, 1); PG8_STAGE(PG8_SB(0, 0), b2, voffB); PG8_STAGE(PG8_SB(0, 1), b2 + hstepB, voffB); PG8_STAGE(PG8_SA(0, 0), a2, voffA);
.LBB0_284:
	s_add_u32 s10, s8, 0xfff00800
	s_addc_u32 s11, s9, -1
	s_add_i32 s55, 0, 0x10000
	s_cmp_eq_u32 s54, 60
	s_cselect_b32 s37, s0, s11
	s_cselect_b32 s36, s1, s10
	s_cselect_b32 s11, s2, s29
	s_cselect_b32 s10, s7, s27
	s_add_i32 s58, 0, 0x14000
	v_add_u32_e32 v142, s55, v161
	v_add_u32_e32 v154, s58, v161
	ds_read_b128 v[130:133], v142
	ds_read_b128 v[134:137], v142 offset:1024
	ds_read_b128 v[138:141], v142 offset:2048
	ds_read_b128 v[142:145], v142 offset:3072
	ds_read_b128 v[172:175], v154
	ds_read_b128 v[188:191], v154 offset:1024
	ds_read_b128 v[218:221], v154 offset:2048
	ds_read_b128 v[222:225], v154 offset:3072
	v_lshl_add_u64 v[154:155], s[8:9], 0, v[150:151]
	s_add_i32 m0, s45, 0xc000
	ds_read_b128 v[226:229], v171
	ds_read_b128 v[230:233], v171 offset:1024
	ds_read_b128 v[234:237], v171 offset:2048
	ds_read_b128 v[238:241], v171 offset:3072
	ds_read_b128 v[242:245], v171 offset:4096
	ds_read_b128 v[246:249], v171 offset:5120
	ds_read_b128 v[250:253], v171 offset:6144
	ds_read_b128 v[206:209], v171 offset:7168
	global_load_lds_dwordx4 v[154:155], off
	v_lshl_add_u64 v[154:155], s[8:9], 0, v[152:153]
	s_add_i32 m0, s45, 0xe000
	s_nop 0
	global_load_lds_dwordx4 v[154:155], off
	s_waitcnt vmcnt(8)
	s_waitcnt lgkmcnt(0)
	s_barrier
	s_setprio 1
	v_mfma_f32_16x16x32_bf16 v[126:129], v[130:133], v[226:229], v[126:129]
	v_mfma_f32_16x16x32_bf16 v[122:125], v[138:141], v[226:229], v[122:125]
	v_mfma_f32_16x16x32_bf16 v[118:121], v[130:133], v[234:237], v[118:121]
	v_mfma_f32_16x16x32_bf16 v[110:113], v[138:141], v[234:237], v[110:113]
	v_mfma_f32_16x16x32_bf16 v[102:105], v[130:133], v[242:245], v[102:105]
	v_mfma_f32_16x16x32_bf16 v[94:97], v[138:141], v[242:245], v[94:97]
	v_mfma_f32_16x16x32_bf16 v[86:89], v[130:133], v[250:253], v[86:89]
	v_mfma_f32_16x16x32_bf16 v[78:81], v[138:141], v[250:253], v[78:81]
	v_mfma_f32_16x16x32_bf16 v[126:129], v[134:137], v[230:233], v[126:129]
	v_mfma_f32_16x16x32_bf16 v[122:125], v[142:145], v[230:233], v[122:125]
	v_mfma_f32_16x16x32_bf16 v[118:121], v[134:137], v[238:241], v[118:121]
	v_mfma_f32_16x16x32_bf16 v[110:113], v[142:145], v[238:241], v[110:113]
	v_mfma_f32_16x16x32_bf16 v[102:105], v[134:137], v[246:249], v[102:105]
	v_mfma_f32_16x16x32_bf16 v[94:97], v[142:145], v[246:249], v[94:97]
	v_mfma_f32_16x16x32_bf16 v[86:89], v[134:137], v[206:209], v[86:89]
	v_mfma_f32_16x16x32_bf16 v[78:81], v[142:145], v[206:209], v[78:81]
	s_setprio 0
	s_setprio 1
	v_mfma_f32_16x16x32_bf16 v[114:117], v[172:175], v[226:229], v[114:117]
	v_mfma_f32_16x16x32_bf16 v[106:109], v[218:221], v[226:229], v[106:109]
	v_mfma_f32_16x16x32_bf16 v[98:101], v[172:175], v[234:237], v[98:101]
	v_mfma_f32_16x16x32_bf16 v[90:93], v[218:221], v[234:237], v[90:93]
	v_mfma_f32_16x16x32_bf16 v[82:85], v[172:175], v[242:245], v[82:85]
	v_mfma_f32_16x16x32_bf16 v[74:77], v[218:221], v[242:245], v[74:77]
	v_mfma_f32_16x16x32_bf16 v[70:73], v[172:175], v[250:253], v[70:73]
	v_mfma_f32_16x16x32_bf16 v[66:69], v[218:221], v[250:253], v[66:69]
	v_mfma_f32_16x16x32_bf16 v[114:117], v[188:191], v[230:233], v[114:117]
	v_mfma_f32_16x16x32_bf16 v[106:109], v[222:225], v[230:233], v[106:109]
	v_mfma_f32_16x16x32_bf16 v[98:101], v[188:191], v[238:241], v[98:101]
	v_mfma_f32_16x16x32_bf16 v[90:93], v[222:225], v[238:241], v[90:93]
	v_mfma_f32_16x16x32_bf16 v[82:85], v[188:191], v[246:249], v[82:85]
	v_mfma_f32_16x16x32_bf16 v[74:77], v[222:225], v[246:249], v[74:77]
	v_mfma_f32_16x16x32_bf16 v[70:73], v[188:191], v[206:209], v[70:73]
	v_mfma_f32_16x16x32_bf16 v[66:69], v[222:225], v[206:209], v[66:69]
	s_setprio 0
	s_barrier
	s_add_i32 s55, s55, s43
	v_lshl_add_u64 v[154:155], s[10:11], 0, v[148:149]
	s_mov_b32 m0, s55
	ds_read_b128 v[206:209], v171 offset:16384
	ds_read_b128 v[226:229], v171 offset:17408
	ds_read_b128 v[230:233], v171 offset:18432
	ds_read_b128 v[234:237], v171 offset:19456
	ds_read_b128 v[238:241], v171 offset:20480
	ds_read_b128 v[242:245], v171 offset:21504
	ds_read_b128 v[246:249], v171 offset:22528
	ds_read_b128 v[250:253], v171 offset:23552
	global_load_lds_dwordx4 v[154:155], off
	s_add_i32 m0, s55, 0x2000
	s_add_u32 s56, s10, 0x100000
	v_lshl_add_u64 v[176:177], s[10:11], 0, v[146:147]
	s_addc_u32 s57, s11, 0
	s_add_i32 s55, s58, s43
	global_load_lds_dwordx4 v[176:177], off
	v_lshl_add_u64 v[194:195], s[56:57], 0, v[148:149]
	s_mov_b32 m0, s55
	v_lshl_add_u64 v[210:211], s[36:37], 0, v[146:147]
	global_load_lds_dwordx4 v[194:195], off
	v_lshl_add_u64 v[194:195], s[56:57], 0, v[146:147]
	s_add_i32 m0, s55, 0x2000
	s_nop 0
	global_load_lds_dwordx4 v[194:195], off
	v_lshl_add_u64 v[194:195], s[36:37], 0, v[148:149]
	s_mov_b32 m0, s45
	s_nop 0
	global_load_lds_dwordx4 v[194:195], off
	s_mov_b32 m0, s46
	s_nop 0
	global_load_lds_dwordx4 v[210:211], off
	s_waitcnt vmcnt(8)
	s_waitcnt lgkmcnt(0)
	s_barrier
; #define PG8_STAGE(bufoff, gbase, voff) do { _Pragma("unroll") for (int _i = 0; _i < 2; ++_i) \
;         __builtin_amdgcn_global_load_lds((const unsigned*)((const char*)(gbase) + (voff)[_i]), (PG8_LAS unsigned*)(lds + (bufoff) + ldsw + _i * 8192), 16, 0, 0); } while (0)
; #define PG8_LDA(dst, b, h) do { _Pragma("unroll") for (int m = 0; m < 4; ++m) _Pragma("unroll") for (int k = 0; k < 2; ++k) dst[m][k] = *(const PG8_LAS bf16x8*)(lds + PG8_SA(b, h) + aoff + m * 2048 + k * 1024); } while (0)
; #define PG8_LDB(dst, b, h) do { _Pragma("unroll") for (int n = 0; n < 2; ++n) _Pragma("unroll") for (int k = 0; k < 2; ++k) dst[n][k] = *(const PG8_LAS bf16x8*)(lds + PG8_SB(b, h) + boff + n * 2048 + k * 1024); } while (0)
; #define PG8_MMA(ai, bj, At, Bt) do { __builtin_amdgcn_s_setprio(1); _Pragma("unroll") for (int m = 0; m < 4; ++m) _Pragma("unroll") for (int n = 0; n < 2; ++n) _Pragma("unroll") for (int k = 0; k < 2; ++k) \
;         acc[ai][bj][m][n] = __builtin_amdgcn_mfma_f32_16x16x32_bf16(Bt[n][k], At[m][k], acc[ai][bj][m][n], 0, 0, 0); __builtin_amdgcn_s_setprio(0); } while (0)
; #define PG8_WAIT_V(n) asm volatile("s_waitcnt vmcnt(" #n ")" ::: "memory")
; #define PG8_WAIT_L(n) asm volatile("s_waitcnt lgkmcnt(" #n ")" ::: "memory")
; #define PG8_BAR __builtin_amdgcn_s_barrier()
; #define PG8_SCHED __builtin_amdgcn_sched_barrier(0)
; template <class Epi, class Sched, bool ALIGN_EPI, int LMASK = -1, int LMASKB = LMASK>
; __device__ __forceinline__ void gemm_phase(PG8_LAS unsigned char* lds, const Gemm g, const Sched& S, const Epi& E) {
;     ...
;             PG8_WAIT_V(8); PG8_WAIT_L(0); PG8_BAR; PG8_MMA(1, 0, At, B0); PG8_MMA(1, 1, At, B1); PG8_BAR; PG8_SCHED;
;             PG8_LDB(B0, 1, 0); PG8_LDB(B1, 1, 1); PG8_SCHED; PG8_LDA(At, 1, 0); PG8_STAGE(PG8_SA(0, 1), a2 + hstepA, voffA);
;             PG8_WAIT_V(8); PG8_WAIT_L(0); PG8_BAR; PG8_MMA(0, 0, At, B0); PG8_MMA(0, 1, At, B1); PG8_BAR; PG8_SCHED;
	s_setprio 1
	v_mfma_f32_16x16x32_bf16 v[62:65], v[130:133], v[206:209], v[62:65]
	v_mfma_f32_16x16x32_bf16 v[58:61], v[138:141], v[206:209], v[58:61]
	v_mfma_f32_16x16x32_bf16 v[54:57], v[130:133], v[230:233], v[54:57]
	v_mfma_f32_16x16x32_bf16 v[46:49], v[138:141], v[230:233], v[46:49]
	v_mfma_f32_16x16x32_bf16 v[38:41], v[130:133], v[238:241], v[38:41]
	v_mfma_f32_16x16x32_bf16 v[30:33], v[138:141], v[238:241], v[30:33]
	v_mfma_f32_16x16x32_bf16 v[22:25], v[130:133], v[246:249], v[22:25]
	v_mfma_f32_16x16x32_bf16 v[14:17], v[138:141], v[246:249], v[14:17]
	v_mfma_f32_16x16x32_bf16 v[62:65], v[134:137], v[226:229], v[62:65]
	v_mfma_f32_16x16x32_bf16 v[58:61], v[142:145], v[226:229], v[58:61]
	v_mfma_f32_16x16x32_bf16 v[54:57], v[134:137], v[234:237], v[54:57]
	v_mfma_f32_16x16x32_bf16 v[46:49], v[142:145], v[234:237], v[46:49]
	v_mfma_f32_16x16x32_bf16 v[38:41], v[134:137], v[242:245], v[38:41]
	v_mfma_f32_16x16x32_bf16 v[30:33], v[142:145], v[242:245], v[30:33]
	v_mfma_f32_16x16x32_bf16 v[22:25], v[134:137], v[250:253], v[22:25]
	v_mfma_f32_16x16x32_bf16 v[14:17], v[142:145], v[250:253], v[14:17]
	s_setprio 0
	s_setprio 1
	v_mfma_f32_16x16x32_bf16 v[50:53], v[172:175], v[206:209], v[50:53]
	v_mfma_f32_16x16x32_bf16 v[42:45], v[218:221], v[206:209], v[42:45]
	v_mfma_f32_16x16x32_bf16 v[34:37], v[172:175], v[230:233], v[34:37]
	v_mfma_f32_16x16x32_bf16 v[26:29], v[218:221], v[230:233], v[26:29]
	v_mfma_f32_16x16x32_bf16 v[18:21], v[172:175], v[238:241], v[18:21]
	v_mfma_f32_16x16x32_bf16 v[10:13], v[218:221], v[238:241], v[10:13]
	v_mfma_f32_16x16x32_bf16 v[6:9], v[172:175], v[246:249], v[6:9]
	v_mfma_f32_16x16x32_bf16 v[2:5], v[218:221], v[246:249], v[2:5]
	v_mfma_f32_16x16x32_bf16 v[50:53], v[188:191], v[226:229], v[50:53]
	v_mfma_f32_16x16x32_bf16 v[42:45], v[222:225], v[226:229], v[42:45]
	v_mfma_f32_16x16x32_bf16 v[34:37], v[188:191], v[234:237], v[34:37]
	v_mfma_f32_16x16x32_bf16 v[26:29], v[222:225], v[234:237], v[26:29]
	v_mfma_f32_16x16x32_bf16 v[18:21], v[188:191], v[242:245], v[18:21]
	v_mfma_f32_16x16x32_bf16 v[10:13], v[222:225], v[242:245], v[10:13]
	v_mfma_f32_16x16x32_bf16 v[6:9], v[188:191], v[250:253], v[6:9]
	v_mfma_f32_16x16x32_bf16 v[2:5], v[222:225], v[250:253], v[2:5]
	s_setprio 0
	s_barrier
	s_add_i32 s55, 0, 0x18000
	s_add_i32 s56, 0, 0x1c000
	v_add_u32_e32 v142, s55, v161
	v_add_u32_e32 v156, s56, v161
	ds_read_b128 v[130:133], v142
	ds_read_b128 v[134:137], v142 offset:1024
	ds_read_b128 v[138:141], v142 offset:2048
	ds_read_b128 v[142:145], v142 offset:3072
	ds_read_b128 v[172:175], v156
	ds_read_b128 v[188:191], v156 offset:1024
	ds_read_b128 v[206:209], v156 offset:2048
	ds_read_b128 v[218:221], v156 offset:3072
	s_add_u32 s36, s36, 0x100000
	s_addc_u32 s37, s37, 0
	s_mov_b32 m0, s47
	v_lshl_add_u64 v[212:213], s[36:37], 0, v[148:149]
	ds_read_b128 v[222:225], v171 offset:32768
	ds_read_b128 v[226:229], v171 offset:33792
	ds_read_b128 v[230:233], v171 offset:34816
	ds_read_b128 v[234:237], v171 offset:35840
	ds_read_b128 v[238:241], v171 offset:36864
	ds_read_b128 v[242:245], v171 offset:37888
	ds_read_b128 v[246:249], v171 offset:38912
	ds_read_b128 v[250:253], v171 offset:39936
	global_load_lds_dwordx4 v[212:213], off
	v_lshl_add_u64 v[212:213], s[36:37], 0, v[146:147]
	s_mov_b32 m0, s48
	s_nop 0
	global_load_lds_dwordx4 v[212:213], off
	s_waitcnt vmcnt(8)
	s_waitcnt lgkmcnt(0)
	s_barrier
	s_setprio 1
	v_mfma_f32_16x16x32_bf16 v[126:129], v[130:133], v[222:225], v[126:129]
	v_mfma_f32_16x16x32_bf16 v[122:125], v[138:141], v[222:225], v[122:125]
	v_mfma_f32_16x16x32_bf16 v[118:121], v[130:133], v[230:233], v[118:121]
	v_mfma_f32_16x16x32_bf16 v[110:113], v[138:141], v[230:233], v[110:113]
	v_mfma_f32_16x16x32_bf16 v[102:105], v[130:133], v[238:241], v[102:105]
	v_mfma_f32_16x16x32_bf16 v[94:97], v[138:141], v[238:241], v[94:97]
	v_mfma_f32_16x16x32_bf16 v[86:89], v[130:133], v[246:249], v[86:89]
	v_mfma_f32_16x16x32_bf16 v[78:81], v[138:141], v[246:249], v[78:81]
	v_mfma_f32_16x16x32_bf16 v[126:129], v[134:137], v[226:229], v[126:129]
	v_mfma_f32_16x16x32_bf16 v[122:125], v[142:145], v[226:229], v[122:125]
	v_mfma_f32_16x16x32_bf16 v[118:121], v[134:137], v[234:237], v[118:121]
	v_mfma_f32_16x16x32_bf16 v[110:113], v[142:145], v[234:237], v[110:113]
	v_mfma_f32_16x16x32_bf16 v[102:105], v[134:137], v[242:245], v[102:105]
	v_mfma_f32_16x16x32_bf16 v[94:97], v[142:145], v[242:245], v[94:97]
	v_mfma_f32_16x16x32_bf16 v[86:89], v[134:137], v[250:253], v[86:89]
	v_mfma_f32_16x16x32_bf16 v[78:81], v[142:145], v[250:253], v[78:81]
	s_setprio 0
	s_setprio 1
	v_mfma_f32_16x16x32_bf16 v[114:117], v[172:175], v[222:225], v[114:117]
	v_mfma_f32_16x16x32_bf16 v[106:109], v[206:209], v[222:225], v[106:109]
	v_mfma_f32_16x16x32_bf16 v[98:101], v[172:175], v[230:233], v[98:101]
	v_mfma_f32_16x16x32_bf16 v[90:93], v[206:209], v[230:233], v[90:93]
	v_mfma_f32_16x16x32_bf16 v[82:85], v[172:175], v[238:241], v[82:85]
	v_mfma_f32_16x16x32_bf16 v[74:77], v[206:209], v[238:241], v[74:77]
	v_mfma_f32_16x16x32_bf16 v[70:73], v[172:175], v[246:249], v[70:73]
	v_mfma_f32_16x16x32_bf16 v[66:69], v[206:209], v[246:249], v[66:69]
	v_mfma_f32_16x16x32_bf16 v[114:117], v[188:191], v[226:229], v[114:117]
	v_mfma_f32_16x16x32_bf16 v[106:109], v[218:221], v[226:229], v[106:109]
	v_mfma_f32_16x16x32_bf16 v[98:101], v[188:191], v[234:237], v[98:101]
	v_mfma_f32_16x16x32_bf16 v[90:93], v[218:221], v[234:237], v[90:93]
	v_mfma_f32_16x16x32_bf16 v[82:85], v[188:191], v[242:245], v[82:85]
	v_mfma_f32_16x16x32_bf16 v[74:77], v[218:221], v[242:245], v[74:77]
	v_mfma_f32_16x16x32_bf16 v[70:73], v[188:191], v[250:253], v[70:73]
	v_mfma_f32_16x16x32_bf16 v[66:69], v[218:221], v[250:253], v[66:69]
	s_setprio 0
	s_barrier
; #define PG8_STAGE(bufoff, gbase, voff) do { _Pragma("unroll") for (int _i = 0; _i < 2; ++_i) \
;         __builtin_amdgcn_global_load_lds((const unsigned*)((const char*)(gbase) + (voff)[_i]), (PG8_LAS unsigned*)(lds + (bufoff) + ldsw + _i * 8192), 16, 0, 0); } while (0)
; #define PG8_LDA(dst, b, h) do { _Pragma("unroll") for (int m = 0; m < 4; ++m) _Pragma("unroll") for (int k = 0; k < 2; ++k) dst[m][k] = *(const PG8_LAS bf16x8*)(lds + PG8_SA(b, h) + aoff + m * 2048 + k * 1024); } while (0)
; #define PG8_MMA(ai, bj, At, Bt) do { __builtin_amdgcn_s_setprio(1); _Pragma("unroll") for (int m = 0; m < 4; ++m) _Pragma("unroll") for (int n = 0; n < 2; ++n) _Pragma("unroll") for (int k = 0; k < 2; ++k) \
;         acc[ai][bj][m][n] = __builtin_amdgcn_mfma_f32_16x16x32_bf16(Bt[n][k], At[m][k], acc[ai][bj][m][n], 0, 0, 0); __builtin_amdgcn_s_setprio(0); } while (0)
; #define PG8_WAIT_V(n) asm volatile("s_waitcnt vmcnt(" #n ")" ::: "memory")
; #define PG8_WAIT_L(n) asm volatile("s_waitcnt lgkmcnt(" #n ")" ::: "memory")
; #define PG8_BAR __builtin_amdgcn_s_barrier()
; #define PG8_SCHED __builtin_amdgcn_sched_barrier(0)
; template <class Epi, class Sched, bool ALIGN_EPI, int LMASK = -1, int LMASKB = LMASK>
; __device__ __forceinline__ void gemm_phase(PG8_LAS unsigned char* lds, const Gemm g, const Sched& S, const Epi& E) {
;     ...
;             PG8_LDA(At, 1, 1); PG8_STAGE(PG8_SB(1, 0), b3, voffB); PG8_STAGE(PG8_SB(1, 1), b3 + hstepB, voffB); PG8_STAGE(PG8_SA(1, 0), a3, voffA);
;             PG8_WAIT_V(8); PG8_WAIT_L(0); PG8_BAR; PG8_MMA(1, 0, At, B0); PG8_MMA(1, 1, At, B1); PG8_BAR; PG8_SCHED;
;         }
;         if constexpr (ALIGN_EPI) { if (wr == 0) PG8_BAR; }
;         E(acc, cur, wr, wc, fr, fq);
;         if (!has_next) break;
	s_add_i32 s36, s55, s43
	v_lshl_add_u64 v[154:155], v[154:155], 0, s[80:81]
	s_mov_b32 m0, s36
	ds_read_b128 v[222:225], v171 offset:49152
	ds_read_b128 v[226:229], v171 offset:50176
	ds_read_b128 v[230:233], v171 offset:51200
	ds_read_b128 v[234:237], v171 offset:52224
	ds_read_b128 v[238:241], v171 offset:53248
	ds_read_b128 v[242:245], v171 offset:54272
	ds_read_b128 v[246:249], v171 offset:55296
	ds_read_b128 v[250:253], v171 offset:56320
	global_load_lds_dwordx4 v[154:155], off
	s_add_i32 m0, s36, 0x2000
	s_add_u32 s10, s10, 0x100800
	v_lshl_add_u64 v[154:155], v[176:177], 0, s[80:81]
	s_addc_u32 s11, s11, 0
	s_add_i32 s36, s56, s43
	global_load_lds_dwordx4 v[154:155], off
	v_lshl_add_u64 v[154:155], s[10:11], 0, v[148:149]
	s_mov_b32 m0, s36
	s_nop 0
	global_load_lds_dwordx4 v[154:155], off
	v_lshl_add_u64 v[154:155], s[10:11], 0, v[146:147]
	s_add_i32 m0, s36, 0x2000
	s_nop 0
	global_load_lds_dwordx4 v[154:155], off
	v_lshl_add_u64 v[154:155], v[194:195], 0, s[80:81]
	s_mov_b32 m0, s49
	s_nop 0
	global_load_lds_dwordx4 v[154:155], off
	v_lshl_add_u64 v[154:155], v[210:211], 0, s[80:81]
	s_mov_b32 m0, s50
	s_nop 0
	global_load_lds_dwordx4 v[154:155], off
	s_waitcnt vmcnt(8)
	s_waitcnt lgkmcnt(0)
	s_barrier
	s_setprio 1
	v_mfma_f32_16x16x32_bf16 v[62:65], v[130:133], v[222:225], v[62:65]
	v_mfma_f32_16x16x32_bf16 v[58:61], v[138:141], v[222:225], v[58:61]
	v_mfma_f32_16x16x32_bf16 v[54:57], v[130:133], v[230:233], v[54:57]
	v_mfma_f32_16x16x32_bf16 v[46:49], v[138:141], v[230:233], v[46:49]
	v_mfma_f32_16x16x32_bf16 v[38:41], v[130:133], v[238:241], v[38:41]
	v_mfma_f32_16x16x32_bf16 v[30:33], v[138:141], v[238:241], v[30:33]
	v_mfma_f32_16x16x32_bf16 v[22:25], v[130:133], v[246:249], v[22:25]
	v_mfma_f32_16x16x32_bf16 v[14:17], v[138:141], v[246:249], v[14:17]
	v_mfma_f32_16x16x32_bf16 v[62:65], v[134:137], v[226:229], v[62:65]
	v_mfma_f32_16x16x32_bf16 v[58:61], v[142:145], v[226:229], v[58:61]
	v_mfma_f32_16x16x32_bf16 v[54:57], v[134:137], v[234:237], v[54:57]
	v_mfma_f32_16x16x32_bf16 v[46:49], v[142:145], v[234:237], v[46:49]
	v_mfma_f32_16x16x32_bf16 v[38:41], v[134:137], v[242:245], v[38:41]
	v_mfma_f32_16x16x32_bf16 v[30:33], v[142:145], v[242:245], v[30:33]
	v_mfma_f32_16x16x32_bf16 v[22:25], v[134:137], v[250:253], v[22:25]
	v_mfma_f32_16x16x32_bf16 v[14:17], v[142:145], v[250:253], v[14:17]
	s_setprio 0
	s_setprio 1
	v_mfma_f32_16x16x32_bf16 v[50:53], v[172:175], v[222:225], v[50:53]
	v_mfma_f32_16x16x32_bf16 v[42:45], v[206:209], v[222:225], v[42:45]
	v_mfma_f32_16x16x32_bf16 v[34:37], v[172:175], v[230:233], v[34:37]
	v_mfma_f32_16x16x32_bf16 v[26:29], v[206:209], v[230:233], v[26:29]
	v_mfma_f32_16x16x32_bf16 v[18:21], v[172:175], v[238:241], v[18:21]
	v_mfma_f32_16x16x32_bf16 v[10:13], v[206:209], v[238:241], v[10:13]
	v_mfma_f32_16x16x32_bf16 v[6:9], v[172:175], v[246:249], v[6:9]
	v_mfma_f32_16x16x32_bf16 v[2:5], v[206:209], v[246:249], v[2:5]
	v_mfma_f32_16x16x32_bf16 v[50:53], v[188:191], v[226:229], v[50:53]
	v_mfma_f32_16x16x32_bf16 v[42:45], v[218:221], v[226:229], v[42:45]
	v_mfma_f32_16x16x32_bf16 v[34:37], v[188:191], v[234:237], v[34:37]
	v_mfma_f32_16x16x32_bf16 v[26:29], v[218:221], v[234:237], v[26:29]
	v_mfma_f32_16x16x32_bf16 v[18:21], v[188:191], v[242:245], v[18:21]
	v_mfma_f32_16x16x32_bf16 v[10:13], v[218:221], v[242:245], v[10:13]
	v_mfma_f32_16x16x32_bf16 v[6:9], v[188:191], v[250:253], v[6:9]
	v_mfma_f32_16x16x32_bf16 v[2:5], v[218:221], v[250:253], v[2:5]
	s_setprio 0
	s_barrier
	s_add_i32 s54, s54, 2
	s_add_u32 s8, s8, 0x1000
	s_addc_u32 s9, s9, 0
	s_add_u32 s27, s27, 0x1000
	s_addc_u32 s29, s29, 0
	s_cmp_gt_u32 s54, 61
	s_cbranch_scc0 .LBB0_284
	s_and_b64 vcc, exec, s[22:23]
	s_cbranch_vccz .LBB0_287
	s_barrier

; #define PG8_STAGE(bufoff, gbase, voff) do { _Pragma("unroll") for (int _i = 0; _i < 2; ++_i) \
;         __builtin_amdgcn_global_load_lds((const unsigned*)((const char*)(gbase) + (voff)[_i]), (PG8_LAS unsigned*)(lds + (bufoff) + ldsw + _i * 8192), 16, 0, 0); } while (0)
; #define PG8_LDA(dst, b, h) do { _Pragma("unroll") for (int m = 0; m < 4; ++m) _Pragma("unroll") for (int k = 0; k < 2; ++k) dst[m][k] = *(const PG8_LAS bf16x8*)(lds + PG8_SA(b, h) + aoff + m * 2048 + k * 1024); } while (0)
; #define PG8_LDB(dst, b, h) do { _Pragma("unroll") for (int n = 0; n < 2; ++n) _Pragma("unroll") for (int k = 0; k < 2; ++k) dst[n][k] = *(const PG8_LAS bf16x8*)(lds + PG8_SB(b, h) + boff + n * 2048 + k * 1024); } while (0)
; #define PG8_MMA(ai, bj, At, Bt) do { __builtin_amdgcn_s_setprio(1); _Pragma("unroll") for (int m = 0; m < 4; ++m) _Pragma("unroll") for (int n = 0; n < 2; ++n) _Pragma("unroll") for (int k = 0; k < 2; ++k) \
;         acc[ai][bj][m][n] = __builtin_amdgcn_mfma_f32_16x16x32_bf16(Bt[n][k], At[m][k], acc[ai][bj][m][n], 0, 0, 0); __builtin_amdgcn_s_setprio(0); } while (0)
; #define PG8_WAIT_V(n) asm volatile("s_waitcnt vmcnt(" #n ")" ::: "memory")
; #define PG8_WAIT_L(n) asm volatile("s_waitcnt lgkmcnt(" #n ")" ::: "memory")
; #define PG8_BAR __builtin_amdgcn_s_barrier()
; #define PG8_SCHED __builtin_amdgcn_sched_barrier(0)
; template <class Epi, class Sched, bool ALIGN_EPI, int LMASK = -1, int LMASKB = LMASK>
; __device__ __forceinline__ void gemm_phase(PG8_LAS unsigned char* lds, const Gemm g, const Sched& S, const Epi& E) {
;     ...
;             const bool last = (t == nt - 2);
;             const char* a1 = cA + (size_t)(t + 1) * kstepA;
;             const char* a2 = last ? nA : cA + (size_t)(t + 2) * kstepA; const char* b2 = last ? nB : cB + (size_t)(t + 2) * kstepB;
;             const char* a3 = a2 + kstepA; const char* b3 = b2 + kstepB;
;             PG8_LDB(B0, 0, 0); PG8_LDB(B1, 0, 1); PG8_SCHED; PG8_LDA(At, 0, 0); PG8_STAGE(PG8_SA(1, 1), a1 + hstepA, voffA);
;             PG8_WAIT_V(8); PG8_WAIT_L(0); PG8_BAR; PG8_MMA(0, 0, At, B0); PG8_MMA(0, 1, At, B1); PG8_BAR; PG8_SCHED;
;             PG8_LDA(At, 0, 1); PG8_STAGE(PG8_SB(0, 0), b2, voffB); PG8_STAGE(PG8_SB(0, 1), b2 + hstepB, voffB); PG8_STAGE(PG8_SA(0, 0), a2, voffA);
.LBB0_580:
	s_add_u32 s30, s28, 0xfff00800
	s_addc_u32 s31, s29, -1
	s_add_i32 s51, 0, 0x10000
	s_cmp_eq_u32 s50, 60
	s_cselect_b32 s35, s19, s31
	s_cselect_b32 s34, s25, s30
	v_add_u32_e32 v146, s51, v149
	s_cselect_b32 s31, s17, s49
	s_cselect_b32 s30, s47, s48
	s_add_i32 s54, 0, 0x14000
	ds_read_b128 v[130:133], v146
	ds_read_b128 v[142:145], v146 offset:1024
	ds_read_b128 v[152:155], v146 offset:2048
	ds_read_b128 v[156:159], v146 offset:3072
	v_add_u32_e32 v146, s54, v149
	ds_read_b128 v[160:163], v146
	ds_read_b128 v[164:167], v146 offset:1024
	ds_read_b128 v[168:171], v146 offset:2048
	ds_read_b128 v[172:175], v146 offset:3072
	v_lshl_add_u64 v[146:147], s[28:29], 0, v[138:139]
	s_add_i32 m0, s27, 0xc000
	ds_read_b128 v[188:191], v151
	ds_read_b128 v[206:209], v151 offset:1024
	ds_read_b128 v[218:221], v151 offset:2048
	ds_read_b128 v[222:225], v151 offset:3072
	ds_read_b128 v[226:229], v151 offset:4096
	ds_read_b128 v[230:233], v151 offset:5120
	ds_read_b128 v[234:237], v151 offset:6144
	ds_read_b128 v[238:241], v151 offset:7168
	global_load_lds_dwordx4 v[146:147], off
	v_lshl_add_u64 v[146:147], s[28:29], 0, v[140:141]
	s_add_i32 m0, s27, 0xe000
	s_nop 0
	global_load_lds_dwordx4 v[146:147], off
	s_waitcnt vmcnt(8)
	s_waitcnt lgkmcnt(0)
	s_barrier
	s_setprio 1
	v_mfma_f32_16x16x32_bf16 v[126:129], v[130:133], v[188:191], v[126:129]
	v_mfma_f32_16x16x32_bf16 v[122:125], v[152:155], v[188:191], v[122:125]
	v_mfma_f32_16x16x32_bf16 v[110:113], v[130:133], v[218:221], v[110:113]
	v_mfma_f32_16x16x32_bf16 v[106:109], v[152:155], v[218:221], v[106:109]
	v_mfma_f32_16x16x32_bf16 v[94:97], v[130:133], v[226:229], v[94:97]
	v_mfma_f32_16x16x32_bf16 v[90:93], v[152:155], v[226:229], v[90:93]
	v_mfma_f32_16x16x32_bf16 v[78:81], v[130:133], v[234:237], v[78:81]
	v_mfma_f32_16x16x32_bf16 v[74:77], v[152:155], v[234:237], v[74:77]
	v_mfma_f32_16x16x32_bf16 v[126:129], v[142:145], v[206:209], v[126:129]
	v_mfma_f32_16x16x32_bf16 v[122:125], v[156:159], v[206:209], v[122:125]
	v_mfma_f32_16x16x32_bf16 v[110:113], v[142:145], v[222:225], v[110:113]
	v_mfma_f32_16x16x32_bf16 v[106:109], v[156:159], v[222:225], v[106:109]
	v_mfma_f32_16x16x32_bf16 v[94:97], v[142:145], v[230:233], v[94:97]
	v_mfma_f32_16x16x32_bf16 v[90:93], v[156:159], v[230:233], v[90:93]
	v_mfma_f32_16x16x32_bf16 v[78:81], v[142:145], v[238:241], v[78:81]
	v_mfma_f32_16x16x32_bf16 v[74:77], v[156:159], v[238:241], v[74:77]
	s_setprio 0
	s_setprio 1
	v_mfma_f32_16x16x32_bf16 v[118:121], v[160:163], v[188:191], v[118:121]
	v_mfma_f32_16x16x32_bf16 v[114:117], v[168:171], v[188:191], v[114:117]
	v_mfma_f32_16x16x32_bf16 v[102:105], v[160:163], v[218:221], v[102:105]
	v_mfma_f32_16x16x32_bf16 v[98:101], v[168:171], v[218:221], v[98:101]
	v_mfma_f32_16x16x32_bf16 v[86:89], v[160:163], v[226:229], v[86:89]
	v_mfma_f32_16x16x32_bf16 v[82:85], v[168:171], v[226:229], v[82:85]
	v_mfma_f32_16x16x32_bf16 v[70:73], v[160:163], v[234:237], v[70:73]
	v_mfma_f32_16x16x32_bf16 v[66:69], v[168:171], v[234:237], v[66:69]
	v_mfma_f32_16x16x32_bf16 v[118:121], v[164:167], v[206:209], v[118:121]
	v_mfma_f32_16x16x32_bf16 v[114:117], v[172:175], v[206:209], v[114:117]
	v_mfma_f32_16x16x32_bf16 v[102:105], v[164:167], v[222:225], v[102:105]
	v_mfma_f32_16x16x32_bf16 v[98:101], v[172:175], v[222:225], v[98:101]
	v_mfma_f32_16x16x32_bf16 v[86:89], v[164:167], v[230:233], v[86:89]
	v_mfma_f32_16x16x32_bf16 v[82:85], v[172:175], v[230:233], v[82:85]
	v_mfma_f32_16x16x32_bf16 v[70:73], v[164:167], v[238:241], v[70:73]
	v_mfma_f32_16x16x32_bf16 v[66:69], v[172:175], v[238:241], v[66:69]
	s_setprio 0
	s_barrier
	s_add_i32 s51, s51, s38
	v_lshl_add_u64 v[146:147], s[30:31], 0, v[134:135]
	s_mov_b32 m0, s51
	ds_read_b128 v[188:191], v151 offset:16384
	ds_read_b128 v[206:209], v151 offset:17408
	ds_read_b128 v[218:221], v151 offset:18432
	ds_read_b128 v[222:225], v151 offset:19456
	ds_read_b128 v[226:229], v151 offset:20480
	ds_read_b128 v[230:233], v151 offset:21504
	ds_read_b128 v[234:237], v151 offset:22528
	ds_read_b128 v[238:241], v151 offset:23552
	global_load_lds_dwordx4 v[146:147], off
	s_add_i32 m0, s51, 0x2000
	s_add_u32 s52, s30, 0x100000
	v_lshl_add_u64 v[176:177], s[30:31], 0, v[136:137]
	s_addc_u32 s53, s31, 0
	s_add_i32 s51, s54, s38
	global_load_lds_dwordx4 v[176:177], off
	v_lshl_add_u64 v[194:195], s[52:53], 0, v[134:135]
	s_mov_b32 m0, s51
	v_lshl_add_u64 v[210:211], s[34:35], 0, v[136:137]
	global_load_lds_dwordx4 v[194:195], off
	v_lshl_add_u64 v[194:195], s[52:53], 0, v[136:137]
	s_add_i32 m0, s51, 0x2000
	s_nop 0
	global_load_lds_dwordx4 v[194:195], off
	v_lshl_add_u64 v[194:195], s[34:35], 0, v[134:135]
	s_mov_b32 m0, s27
	s_nop 0
	global_load_lds_dwordx4 v[194:195], off
	s_mov_b32 m0, s39
	s_nop 0
	global_load_lds_dwordx4 v[210:211], off
	s_waitcnt vmcnt(8)
	s_waitcnt lgkmcnt(0)
	s_barrier
; #define PG8_STAGE(bufoff, gbase, voff) do { _Pragma("unroll") for (int _i = 0; _i < 2; ++_i) \
;         __builtin_amdgcn_global_load_lds((const unsigned*)((const char*)(gbase) + (voff)[_i]), (PG8_LAS unsigned*)(lds + (bufoff) + ldsw + _i * 8192), 16, 0, 0); } while (0)
; #define PG8_LDA(dst, b, h) do { _Pragma("unroll") for (int m = 0; m < 4; ++m) _Pragma("unroll") for (int k = 0; k < 2; ++k) dst[m][k] = *(const PG8_LAS bf16x8*)(lds + PG8_SA(b, h) + aoff + m * 2048 + k * 1024); } while (0)
; #define PG8_LDB(dst, b, h) do { _Pragma("unroll") for (int n = 0; n < 2; ++n) _Pragma("unroll") for (int k = 0; k < 2; ++k) dst[n][k] = *(const PG8_LAS bf16x8*)(lds + PG8_SB(b, h) + boff + n * 2048 + k * 1024); } while (0)
; #define PG8_MMA(ai, bj, At, Bt) do { __builtin_amdgcn_s_setprio(1); _Pragma("unroll") for (int m = 0; m < 4; ++m) _Pragma("unroll") for (int n = 0; n < 2; ++n) _Pragma("unroll") for (int k = 0; k < 2; ++k) \
;         acc[ai][bj][m][n] = __builtin_amdgcn_mfma_f32_16x16x32_bf16(Bt[n][k], At[m][k], acc[ai][bj][m][n], 0, 0, 0); __builtin_amdgcn_s_setprio(0); } while (0)
; #define PG8_WAIT_V(n) asm volatile("s_waitcnt vmcnt(" #n ")" ::: "memory")
; #define PG8_WAIT_L(n) asm volatile("s_waitcnt lgkmcnt(" #n ")" ::: "memory")
; #define PG8_BAR __builtin_amdgcn_s_barrier()
; #define PG8_SCHED __builtin_amdgcn_sched_barrier(0)
; template <class Epi, class Sched, bool ALIGN_EPI, int LMASK = -1, int LMASKB = LMASK>
; __device__ __forceinline__ void gemm_phase(PG8_LAS unsigned char* lds, const Gemm g, const Sched& S, const Epi& E) {
;     ...
;             PG8_WAIT_V(8); PG8_WAIT_L(0); PG8_BAR; PG8_MMA(1, 0, At, B0); PG8_MMA(1, 1, At, B1); PG8_BAR; PG8_SCHED;
;             PG8_LDB(B0, 1, 0); PG8_LDB(B1, 1, 1); PG8_SCHED; PG8_LDA(At, 1, 0); PG8_STAGE(PG8_SA(0, 1), a2 + hstepA, voffA);
;             PG8_WAIT_V(8); PG8_WAIT_L(0); PG8_BAR; PG8_MMA(0, 0, At, B0); PG8_MMA(0, 1, At, B1); PG8_BAR; PG8_SCHED;
	s_setprio 1
	v_mfma_f32_16x16x32_bf16 v[62:65], v[130:133], v[188:191], v[62:65]
	v_mfma_f32_16x16x32_bf16 v[58:61], v[152:155], v[188:191], v[58:61]
	v_mfma_f32_16x16x32_bf16 v[46:49], v[130:133], v[218:221], v[46:49]
	v_mfma_f32_16x16x32_bf16 v[42:45], v[152:155], v[218:221], v[42:45]
	v_mfma_f32_16x16x32_bf16 v[30:33], v[130:133], v[226:229], v[30:33]
	v_mfma_f32_16x16x32_bf16 v[26:29], v[152:155], v[226:229], v[26:29]
	v_mfma_f32_16x16x32_bf16 v[14:17], v[130:133], v[234:237], v[14:17]
	v_mfma_f32_16x16x32_bf16 v[10:13], v[152:155], v[234:237], v[10:13]
	v_mfma_f32_16x16x32_bf16 v[62:65], v[142:145], v[206:209], v[62:65]
	v_mfma_f32_16x16x32_bf16 v[58:61], v[156:159], v[206:209], v[58:61]
	v_mfma_f32_16x16x32_bf16 v[46:49], v[142:145], v[222:225], v[46:49]
	v_mfma_f32_16x16x32_bf16 v[42:45], v[156:159], v[222:225], v[42:45]
	v_mfma_f32_16x16x32_bf16 v[30:33], v[142:145], v[230:233], v[30:33]
	v_mfma_f32_16x16x32_bf16 v[26:29], v[156:159], v[230:233], v[26:29]
	v_mfma_f32_16x16x32_bf16 v[14:17], v[142:145], v[238:241], v[14:17]
	v_mfma_f32_16x16x32_bf16 v[10:13], v[156:159], v[238:241], v[10:13]
	s_setprio 0
	s_setprio 1
	v_mfma_f32_16x16x32_bf16 v[54:57], v[160:163], v[188:191], v[54:57]
	v_mfma_f32_16x16x32_bf16 v[50:53], v[168:171], v[188:191], v[50:53]
	v_mfma_f32_16x16x32_bf16 v[38:41], v[160:163], v[218:221], v[38:41]
	v_mfma_f32_16x16x32_bf16 v[34:37], v[168:171], v[218:221], v[34:37]
	v_mfma_f32_16x16x32_bf16 v[22:25], v[160:163], v[226:229], v[22:25]
	v_mfma_f32_16x16x32_bf16 v[18:21], v[168:171], v[226:229], v[18:21]
	v_mfma_f32_16x16x32_bf16 v[6:9], v[160:163], v[234:237], v[6:9]
	v_mfma_f32_16x16x32_bf16 v[2:5], v[168:171], v[234:237], v[2:5]
	v_mfma_f32_16x16x32_bf16 v[54:57], v[164:167], v[206:209], v[54:57]
	v_mfma_f32_16x16x32_bf16 v[50:53], v[172:175], v[206:209], v[50:53]
	v_mfma_f32_16x16x32_bf16 v[38:41], v[164:167], v[222:225], v[38:41]
	v_mfma_f32_16x16x32_bf16 v[34:37], v[172:175], v[222:225], v[34:37]
	v_mfma_f32_16x16x32_bf16 v[22:25], v[164:167], v[230:233], v[22:25]
	v_mfma_f32_16x16x32_bf16 v[18:21], v[172:175], v[230:233], v[18:21]
	v_mfma_f32_16x16x32_bf16 v[6:9], v[164:167], v[238:241], v[6:9]
	v_mfma_f32_16x16x32_bf16 v[2:5], v[172:175], v[238:241], v[2:5]
	s_setprio 0
	s_barrier
	s_add_i32 s51, 0, 0x18000
	s_add_i32 s52, 0, 0x1c000
	v_add_u32_e32 v156, s51, v149
	v_add_u32_e32 v172, s52, v149
	ds_read_b128 v[130:133], v156
	ds_read_b128 v[142:145], v156 offset:1024
	ds_read_b128 v[152:155], v156 offset:2048
	ds_read_b128 v[156:159], v156 offset:3072
	ds_read_b128 v[160:163], v172
	ds_read_b128 v[164:167], v172 offset:1024
	ds_read_b128 v[168:171], v172 offset:2048
	ds_read_b128 v[172:175], v172 offset:3072
	s_add_u32 s34, s34, 0x100000
	s_addc_u32 s35, s35, 0
	s_mov_b32 m0, s40
	v_lshl_add_u64 v[212:213], s[34:35], 0, v[134:135]
	ds_read_b128 v[188:191], v151 offset:32768
	ds_read_b128 v[206:209], v151 offset:33792
	ds_read_b128 v[218:221], v151 offset:34816
	ds_read_b128 v[222:225], v151 offset:35840
	ds_read_b128 v[226:229], v151 offset:36864
	ds_read_b128 v[230:233], v151 offset:37888
	ds_read_b128 v[234:237], v151 offset:38912
	ds_read_b128 v[238:241], v151 offset:39936
	global_load_lds_dwordx4 v[212:213], off
	v_lshl_add_u64 v[212:213], s[34:35], 0, v[136:137]
	s_mov_b32 m0, s41
	s_nop 0
	global_load_lds_dwordx4 v[212:213], off
	s_waitcnt vmcnt(8)
	s_waitcnt lgkmcnt(0)
	s_barrier
	s_setprio 1
	v_mfma_f32_16x16x32_bf16 v[126:129], v[130:133], v[188:191], v[126:129]
	v_mfma_f32_16x16x32_bf16 v[122:125], v[152:155], v[188:191], v[122:125]
	v_mfma_f32_16x16x32_bf16 v[110:113], v[130:133], v[218:221], v[110:113]
	v_mfma_f32_16x16x32_bf16 v[106:109], v[152:155], v[218:221], v[106:109]
	v_mfma_f32_16x16x32_bf16 v[94:97], v[130:133], v[226:229], v[94:97]
	v_mfma_f32_16x16x32_bf16 v[90:93], v[152:155], v[226:229], v[90:93]
	v_mfma_f32_16x16x32_bf16 v[78:81], v[130:133], v[234:237], v[78:81]
	v_mfma_f32_16x16x32_bf16 v[74:77], v[152:155], v[234:237], v[74:77]
	v_mfma_f32_16x16x32_bf16 v[126:129], v[142:145], v[206:209], v[126:129]
	v_mfma_f32_16x16x32_bf16 v[122:125], v[156:159], v[206:209], v[122:125]
	v_mfma_f32_16x16x32_bf16 v[110:113], v[142:145], v[222:225], v[110:113]
	v_mfma_f32_16x16x32_bf16 v[106:109], v[156:159], v[222:225], v[106:109]
	v_mfma_f32_16x16x32_bf16 v[94:97], v[142:145], v[230:233], v[94:97]
	v_mfma_f32_16x16x32_bf16 v[90:93], v[156:159], v[230:233], v[90:93]
	v_mfma_f32_16x16x32_bf16 v[78:81], v[142:145], v[238:241], v[78:81]
	v_mfma_f32_16x16x32_bf16 v[74:77], v[156:159], v[238:241], v[74:77]
	s_setprio 0
	s_setprio 1
	v_mfma_f32_16x16x32_bf16 v[118:121], v[160:163], v[188:191], v[118:121]
	v_mfma_f32_16x16x32_bf16 v[114:117], v[168:171], v[188:191], v[114:117]
	v_mfma_f32_16x16x32_bf16 v[102:105], v[160:163], v[218:221], v[102:105]
	v_mfma_f32_16x16x32_bf16 v[98:101], v[168:171], v[218:221], v[98:101]
	v_mfma_f32_16x16x32_bf16 v[86:89], v[160:163], v[226:229], v[86:89]
	v_mfma_f32_16x16x32_bf16 v[82:85], v[168:171], v[226:229], v[82:85]
	v_mfma_f32_16x16x32_bf16 v[70:73], v[160:163], v[234:237], v[70:73]
	v_mfma_f32_16x16x32_bf16 v[66:69], v[168:171], v[234:237], v[66:69]
	v_mfma_f32_16x16x32_bf16 v[118:121], v[164:167], v[206:209], v[118:121]
	v_mfma_f32_16x16x32_bf16 v[114:117], v[172:175], v[206:209], v[114:117]
	v_mfma_f32_16x16x32_bf16 v[102:105], v[164:167], v[222:225], v[102:105]
	v_mfma_f32_16x16x32_bf16 v[98:101], v[172:175], v[222:225], v[98:101]
	v_mfma_f32_16x16x32_bf16 v[86:89], v[164:167], v[230:233], v[86:89]
	v_mfma_f32_16x16x32_bf16 v[82:85], v[172:175], v[230:233], v[82:85]
	v_mfma_f32_16x16x32_bf16 v[70:73], v[164:167], v[238:241], v[70:73]
	v_mfma_f32_16x16x32_bf16 v[66:69], v[172:175], v[238:241], v[66:69]
	s_setprio 0
	s_barrier
; #define PG8_STAGE(bufoff, gbase, voff) do { _Pragma("unroll") for (int _i = 0; _i < 2; ++_i) \
;         __builtin_amdgcn_global_load_lds((const unsigned*)((const char*)(gbase) + (voff)[_i]), (PG8_LAS unsigned*)(lds + (bufoff) + ldsw + _i * 8192), 16, 0, 0); } while (0)
; #define PG8_LDA(dst, b, h) do { _Pragma("unroll") for (int m = 0; m < 4; ++m) _Pragma("unroll") for (int k = 0; k < 2; ++k) dst[m][k] = *(const PG8_LAS bf16x8*)(lds + PG8_SA(b, h) + aoff + m * 2048 + k * 1024); } while (0)
; #define PG8_MMA(ai, bj, At, Bt) do { __builtin_amdgcn_s_setprio(1); _Pragma("unroll") for (int m = 0; m < 4; ++m) _Pragma("unroll") for (int n = 0; n < 2; ++n) _Pragma("unroll") for (int k = 0; k < 2; ++k) \
;         acc[ai][bj][m][n] = __builtin_amdgcn_mfma_f32_16x16x32_bf16(Bt[n][k], At[m][k], acc[ai][bj][m][n], 0, 0, 0); __builtin_amdgcn_s_setprio(0); } while (0)
; #define PG8_WAIT_V(n) asm volatile("s_waitcnt vmcnt(" #n ")" ::: "memory")
; #define PG8_WAIT_L(n) asm volatile("s_waitcnt lgkmcnt(" #n ")" ::: "memory")
; #define PG8_BAR __builtin_amdgcn_s_barrier()
; #define PG8_SCHED __builtin_amdgcn_sched_barrier(0)
; template <class Epi, class Sched, bool ALIGN_EPI, int LMASK = -1, int LMASKB = LMASK>
; __device__ __forceinline__ void gemm_phase(PG8_LAS unsigned char* lds, const Gemm g, const Sched& S, const Epi& E) {
;     ...
;             PG8_LDA(At, 1, 1); PG8_STAGE(PG8_SB(1, 0), b3, voffB); PG8_STAGE(PG8_SB(1, 1), b3 + hstepB, voffB); PG8_STAGE(PG8_SA(1, 0), a3, voffA);
;             PG8_WAIT_V(8); PG8_WAIT_L(0); PG8_BAR; PG8_MMA(1, 0, At, B0); PG8_MMA(1, 1, At, B1); PG8_BAR; PG8_SCHED;
;         }
;         if constexpr (ALIGN_EPI) { if (wr == 0) PG8_BAR; }
;         E(acc, cur, wr, wc, fr, fq);
;         if (!has_next) break;
	s_add_i32 s34, s51, s38
	v_lshl_add_u64 v[146:147], v[146:147], 0, s[80:81]
	s_mov_b32 m0, s34
	ds_read_b128 v[188:191], v151 offset:49152
	ds_read_b128 v[206:209], v151 offset:50176
	ds_read_b128 v[218:221], v151 offset:51200
	ds_read_b128 v[222:225], v151 offset:52224
	ds_read_b128 v[226:229], v151 offset:53248
	ds_read_b128 v[230:233], v151 offset:54272
	ds_read_b128 v[234:237], v151 offset:55296
	ds_read_b128 v[238:241], v151 offset:56320
	global_load_lds_dwordx4 v[146:147], off
	s_add_i32 m0, s34, 0x2000
	s_add_u32 s30, s30, 0x100800
	v_lshl_add_u64 v[146:147], v[176:177], 0, s[80:81]
	s_addc_u32 s31, s31, 0
	s_add_i32 s34, s52, s38
	global_load_lds_dwordx4 v[146:147], off
	v_lshl_add_u64 v[146:147], s[30:31], 0, v[134:135]
	s_mov_b32 m0, s34
	s_nop 0
	global_load_lds_dwordx4 v[146:147], off
	v_lshl_add_u64 v[146:147], s[30:31], 0, v[136:137]
	s_add_i32 m0, s34, 0x2000
	s_nop 0
	global_load_lds_dwordx4 v[146:147], off
	v_lshl_add_u64 v[146:147], v[194:195], 0, s[80:81]
	s_mov_b32 m0, s42
	s_nop 0
	global_load_lds_dwordx4 v[146:147], off
	v_lshl_add_u64 v[146:147], v[210:211], 0, s[80:81]
	s_mov_b32 m0, s43
	s_nop 0
	global_load_lds_dwordx4 v[146:147], off
	s_waitcnt vmcnt(8)
	s_waitcnt lgkmcnt(0)
	s_barrier
	s_setprio 1
	v_mfma_f32_16x16x32_bf16 v[62:65], v[130:133], v[188:191], v[62:65]
	v_mfma_f32_16x16x32_bf16 v[58:61], v[152:155], v[188:191], v[58:61]
	v_mfma_f32_16x16x32_bf16 v[46:49], v[130:133], v[218:221], v[46:49]
	v_mfma_f32_16x16x32_bf16 v[42:45], v[152:155], v[218:221], v[42:45]
	v_mfma_f32_16x16x32_bf16 v[30:33], v[130:133], v[226:229], v[30:33]
	v_mfma_f32_16x16x32_bf16 v[26:29], v[152:155], v[226:229], v[26:29]
	v_mfma_f32_16x16x32_bf16 v[14:17], v[130:133], v[234:237], v[14:17]
	v_mfma_f32_16x16x32_bf16 v[10:13], v[152:155], v[234:237], v[10:13]
	v_mfma_f32_16x16x32_bf16 v[62:65], v[142:145], v[206:209], v[62:65]
	v_mfma_f32_16x16x32_bf16 v[58:61], v[156:159], v[206:209], v[58:61]
	v_mfma_f32_16x16x32_bf16 v[46:49], v[142:145], v[222:225], v[46:49]
	v_mfma_f32_16x16x32_bf16 v[42:45], v[156:159], v[222:225], v[42:45]
	v_mfma_f32_16x16x32_bf16 v[30:33], v[142:145], v[230:233], v[30:33]
	v_mfma_f32_16x16x32_bf16 v[26:29], v[156:159], v[230:233], v[26:29]
	v_mfma_f32_16x16x32_bf16 v[14:17], v[142:145], v[238:241], v[14:17]
	v_mfma_f32_16x16x32_bf16 v[10:13], v[156:159], v[238:241], v[10:13]
	s_setprio 0
	s_setprio 1
	v_mfma_f32_16x16x32_bf16 v[54:57], v[160:163], v[188:191], v[54:57]
	v_mfma_f32_16x16x32_bf16 v[50:53], v[168:171], v[188:191], v[50:53]
	v_mfma_f32_16x16x32_bf16 v[38:41], v[160:163], v[218:221], v[38:41]
	v_mfma_f32_16x16x32_bf16 v[34:37], v[168:171], v[218:221], v[34:37]
	v_mfma_f32_16x16x32_bf16 v[22:25], v[160:163], v[226:229], v[22:25]
	v_mfma_f32_16x16x32_bf16 v[18:21], v[168:171], v[226:229], v[18:21]
	v_mfma_f32_16x16x32_bf16 v[6:9], v[160:163], v[234:237], v[6:9]
	v_mfma_f32_16x16x32_bf16 v[2:5], v[168:171], v[234:237], v[2:5]
	v_mfma_f32_16x16x32_bf16 v[54:57], v[164:167], v[206:209], v[54:57]
	v_mfma_f32_16x16x32_bf16 v[50:53], v[172:175], v[206:209], v[50:53]
	v_mfma_f32_16x16x32_bf16 v[38:41], v[164:167], v[222:225], v[38:41]
	v_mfma_f32_16x16x32_bf16 v[34:37], v[172:175], v[222:225], v[34:37]
	v_mfma_f32_16x16x32_bf16 v[22:25], v[164:167], v[230:233], v[22:25]
	v_mfma_f32_16x16x32_bf16 v[18:21], v[172:175], v[230:233], v[18:21]
	v_mfma_f32_16x16x32_bf16 v[6:9], v[164:167], v[238:241], v[6:9]
	v_mfma_f32_16x16x32_bf16 v[2:5], v[172:175], v[238:241], v[2:5]
	s_setprio 0
	s_barrier
	s_add_i32 s50, s50, 2
	s_add_u32 s28, s28, 0x1000
	s_addc_u32 s29, s29, 0
	s_add_u32 s48, s48, 0x1000
	s_addc_u32 s49, s49, 0
	s_cmp_gt_u32 s50, 61
	s_cbranch_scc0 .LBB0_580
	s_and_b64 vcc, exec, s[14:15]
	s_cbranch_vccz .LBB0_583
	s_barrier

; #define PG8_STAGE(bufoff, gbase, voff) do { _Pragma("unroll") for (int _i = 0; _i < 2; ++_i) \
;         __builtin_amdgcn_global_load_lds((const unsigned*)((const char*)(gbase) + (voff)[_i]), (PG8_LAS unsigned*)(lds + (bufoff) + ldsw + _i * 8192), 16, 0, 0); } while (0)
; #define PG8_LDA(dst, b, h) do { _Pragma("unroll") for (int m = 0; m < 4; ++m) _Pragma("unroll") for (int k = 0; k < 2; ++k) dst[m][k] = *(const PG8_LAS bf16x8*)(lds + PG8_SA(b, h) + aoff + m * 2048 + k * 1024); } while (0)
; #define PG8_LDB(dst, b, h) do { _Pragma("unroll") for (int n = 0; n < 2; ++n) _Pragma("unroll") for (int k = 0; k < 2; ++k) dst[n][k] = *(const PG8_LAS bf16x8*)(lds + PG8_SB(b, h) + boff + n * 2048 + k * 1024); } while (0)
; #define PG8_MMA(ai, bj, At, Bt) do { __builtin_amdgcn_s_setprio(1); _Pragma("unroll") for (int m = 0; m < 4; ++m) _Pragma("unroll") for (int n = 0; n < 2; ++n) _Pragma("unroll") for (int k = 0; k < 2; ++k) \
;         acc[ai][bj][m][n] = __builtin_amdgcn_mfma_f32_16x16x32_bf16(Bt[n][k], At[m][k], acc[ai][bj][m][n], 0, 0, 0); __builtin_amdgcn_s_setprio(0); } while (0)
; #define PG8_WAIT_V(n) asm volatile("s_waitcnt vmcnt(" #n ")" ::: "memory")
; #define PG8_WAIT_L(n) asm volatile("s_waitcnt lgkmcnt(" #n ")" ::: "memory")
; #define PG8_BAR __builtin_amdgcn_s_barrier()
; #define PG8_SCHED __builtin_amdgcn_sched_barrier(0)
; template <class Epi, class Sched, bool ALIGN_EPI, int LMASK = -1, int LMASKB = LMASK>
; __device__ __forceinline__ void gemm_phase(PG8_LAS unsigned char* lds, const Gemm g, const Sched& S, const Epi& E) {
;     ...
;             const bool last = (t == nt - 2);
;             const char* a1 = cA + (size_t)(t + 1) * kstepA;
;             const char* a2 = last ? nA : cA + (size_t)(t + 2) * kstepA; const char* b2 = last ? nB : cB + (size_t)(t + 2) * kstepB;
;             const char* a3 = a2 + kstepA; const char* b3 = b2 + kstepB;
;             PG8_LDB(B0, 0, 0); PG8_LDB(B1, 0, 1); PG8_SCHED; PG8_LDA(At, 0, 0); PG8_STAGE(PG8_SA(1, 1), a1 + hstepA, voffA);
;             PG8_WAIT_V(8); PG8_WAIT_L(0); PG8_BAR; PG8_MMA(0, 0, At, B0); PG8_MMA(0, 1, At, B1); PG8_BAR; PG8_SCHED;
;             PG8_LDA(At, 0, 1); PG8_STAGE(PG8_SB(0, 0), b2, voffB); PG8_STAGE(PG8_SB(0, 1), b2 + hstepB, voffB); PG8_STAGE(PG8_SA(0, 0), a2, voffA);
.LBB0_678:
	s_add_u32 s26, s24, 0xfff00800
	s_addc_u32 s27, s25, -1
	s_add_i32 s50, 0, 0x10000
	s_cmp_eq_u32 s49, 60
	s_cselect_b32 s29, s1, s27
	s_cselect_b32 s28, s2, s26
	s_cselect_b32 s27, s15, s48
	s_cselect_b32 s26, s17, s47
	s_add_i32 s52, 0, 0x14000
	v_add_u32_e32 v154, s50, v143
	v_add_u32_e32 v170, s52, v143
	ds_read_b128 v[138:141], v154
	ds_read_b128 v[146:149], v154 offset:1024
	ds_read_b128 v[150:153], v154 offset:2048
	ds_read_b128 v[154:157], v154 offset:3072
	ds_read_b128 v[158:161], v170
	ds_read_b128 v[162:165], v170 offset:1024
	ds_read_b128 v[166:169], v170 offset:2048
	ds_read_b128 v[170:173], v170 offset:3072
	v_lshl_add_u64 v[194:195], s[24:25], 0, v[134:135]
	s_add_i32 m0, s23, 0xc000
	ds_read_b128 v[174:177], v145
	ds_read_b128 v[188:191], v145 offset:1024
	ds_read_b128 v[206:209], v145 offset:2048
	ds_read_b128 v[218:221], v145 offset:3072
	ds_read_b128 v[222:225], v145 offset:4096
	ds_read_b128 v[226:229], v145 offset:5120
	ds_read_b128 v[230:233], v145 offset:6144
	ds_read_b128 v[234:237], v145 offset:7168
	global_load_lds_dwordx4 v[194:195], off
	v_lshl_add_u64 v[194:195], s[24:25], 0, v[136:137]
	s_add_i32 m0, s23, 0xe000
	s_nop 0
	global_load_lds_dwordx4 v[194:195], off
	s_waitcnt vmcnt(8)
	s_waitcnt lgkmcnt(0)
	s_barrier
	s_setprio 1
	v_mfma_f32_16x16x32_bf16 v[126:129], v[138:141], v[174:177], v[126:129]
	v_mfma_f32_16x16x32_bf16 v[122:125], v[150:153], v[174:177], v[122:125]
	v_mfma_f32_16x16x32_bf16 v[110:113], v[138:141], v[206:209], v[110:113]
	v_mfma_f32_16x16x32_bf16 v[106:109], v[150:153], v[206:209], v[106:109]
	v_mfma_f32_16x16x32_bf16 v[94:97], v[138:141], v[222:225], v[94:97]
	v_mfma_f32_16x16x32_bf16 v[90:93], v[150:153], v[222:225], v[90:93]
	v_mfma_f32_16x16x32_bf16 v[78:81], v[138:141], v[230:233], v[78:81]
	v_mfma_f32_16x16x32_bf16 v[74:77], v[150:153], v[230:233], v[74:77]
	v_mfma_f32_16x16x32_bf16 v[126:129], v[146:149], v[188:191], v[126:129]
	v_mfma_f32_16x16x32_bf16 v[122:125], v[154:157], v[188:191], v[122:125]
	v_mfma_f32_16x16x32_bf16 v[110:113], v[146:149], v[218:221], v[110:113]
	v_mfma_f32_16x16x32_bf16 v[106:109], v[154:157], v[218:221], v[106:109]
	v_mfma_f32_16x16x32_bf16 v[94:97], v[146:149], v[226:229], v[94:97]
	v_mfma_f32_16x16x32_bf16 v[90:93], v[154:157], v[226:229], v[90:93]
	v_mfma_f32_16x16x32_bf16 v[78:81], v[146:149], v[234:237], v[78:81]
	v_mfma_f32_16x16x32_bf16 v[74:77], v[154:157], v[234:237], v[74:77]
	s_setprio 0
	s_setprio 1
	v_mfma_f32_16x16x32_bf16 v[118:121], v[158:161], v[174:177], v[118:121]
	v_mfma_f32_16x16x32_bf16 v[114:117], v[166:169], v[174:177], v[114:117]
	v_mfma_f32_16x16x32_bf16 v[102:105], v[158:161], v[206:209], v[102:105]
	v_mfma_f32_16x16x32_bf16 v[98:101], v[166:169], v[206:209], v[98:101]
	v_mfma_f32_16x16x32_bf16 v[86:89], v[158:161], v[222:225], v[86:89]
	v_mfma_f32_16x16x32_bf16 v[82:85], v[166:169], v[222:225], v[82:85]
	v_mfma_f32_16x16x32_bf16 v[70:73], v[158:161], v[230:233], v[70:73]
	v_mfma_f32_16x16x32_bf16 v[66:69], v[166:169], v[230:233], v[66:69]
	v_mfma_f32_16x16x32_bf16 v[118:121], v[162:165], v[188:191], v[118:121]
	v_mfma_f32_16x16x32_bf16 v[114:117], v[170:173], v[188:191], v[114:117]
	v_mfma_f32_16x16x32_bf16 v[102:105], v[162:165], v[218:221], v[102:105]
	v_mfma_f32_16x16x32_bf16 v[98:101], v[170:173], v[218:221], v[98:101]
	v_mfma_f32_16x16x32_bf16 v[86:89], v[162:165], v[226:229], v[86:89]
	v_mfma_f32_16x16x32_bf16 v[82:85], v[170:173], v[226:229], v[82:85]
	v_mfma_f32_16x16x32_bf16 v[70:73], v[162:165], v[234:237], v[70:73]
	v_mfma_f32_16x16x32_bf16 v[66:69], v[170:173], v[234:237], v[66:69]
	s_setprio 0
	s_barrier
	s_add_i32 s50, s50, s38
	v_lshl_add_u64 v[194:195], s[26:27], 0, v[130:131]
	s_mov_b32 m0, s50
	ds_read_b128 v[174:177], v145 offset:16384
	ds_read_b128 v[188:191], v145 offset:17408
	ds_read_b128 v[206:209], v145 offset:18432
	ds_read_b128 v[218:221], v145 offset:19456
	ds_read_b128 v[222:225], v145 offset:20480
	ds_read_b128 v[226:229], v145 offset:21504
	ds_read_b128 v[230:233], v145 offset:22528
	ds_read_b128 v[234:237], v145 offset:23552
	global_load_lds_dwordx4 v[194:195], off
	s_add_i32 m0, s50, 0x2000
	s_add_u32 s50, s26, 0x100000
	v_lshl_add_u64 v[210:211], s[26:27], 0, v[132:133]
	s_addc_u32 s51, s27, 0
	s_add_i32 s52, s52, s38
	global_load_lds_dwordx4 v[210:211], off
	v_lshl_add_u64 v[212:213], s[50:51], 0, v[130:131]
	s_mov_b32 m0, s52
	v_lshl_add_u64 v[238:239], s[28:29], 0, v[132:133]
	global_load_lds_dwordx4 v[212:213], off
	v_lshl_add_u64 v[212:213], s[50:51], 0, v[132:133]
	s_add_i32 m0, s52, 0x2000
	s_nop 0
	global_load_lds_dwordx4 v[212:213], off
	v_lshl_add_u64 v[212:213], s[28:29], 0, v[130:131]
	s_mov_b32 m0, s23
	s_nop 0
	global_load_lds_dwordx4 v[212:213], off
	s_mov_b32 m0, s39
	s_nop 0
	global_load_lds_dwordx4 v[238:239], off
	s_waitcnt vmcnt(8)
	s_waitcnt lgkmcnt(0)
	s_barrier
; #define PG8_STAGE(bufoff, gbase, voff) do { _Pragma("unroll") for (int _i = 0; _i < 2; ++_i) \
;         __builtin_amdgcn_global_load_lds((const unsigned*)((const char*)(gbase) + (voff)[_i]), (PG8_LAS unsigned*)(lds + (bufoff) + ldsw + _i * 8192), 16, 0, 0); } while (0)
; #define PG8_LDA(dst, b, h) do { _Pragma("unroll") for (int m = 0; m < 4; ++m) _Pragma("unroll") for (int k = 0; k < 2; ++k) dst[m][k] = *(const PG8_LAS bf16x8*)(lds + PG8_SA(b, h) + aoff + m * 2048 + k * 1024); } while (0)
; #define PG8_LDB(dst, b, h) do { _Pragma("unroll") for (int n = 0; n < 2; ++n) _Pragma("unroll") for (int k = 0; k < 2; ++k) dst[n][k] = *(const PG8_LAS bf16x8*)(lds + PG8_SB(b, h) + boff + n * 2048 + k * 1024); } while (0)
; #define PG8_MMA(ai, bj, At, Bt) do { __builtin_amdgcn_s_setprio(1); _Pragma("unroll") for (int m = 0; m < 4; ++m) _Pragma("unroll") for (int n = 0; n < 2; ++n) _Pragma("unroll") for (int k = 0; k < 2; ++k) \
;         acc[ai][bj][m][n] = __builtin_amdgcn_mfma_f32_16x16x32_bf16(Bt[n][k], At[m][k], acc[ai][bj][m][n], 0, 0, 0); __builtin_amdgcn_s_setprio(0); } while (0)
; #define PG8_WAIT_V(n) asm volatile("s_waitcnt vmcnt(" #n ")" ::: "memory")
; #define PG8_WAIT_L(n) asm volatile("s_waitcnt lgkmcnt(" #n ")" ::: "memory")
; #define PG8_BAR __builtin_amdgcn_s_barrier()
; #define PG8_SCHED __builtin_amdgcn_sched_barrier(0)
; template <class Epi, class Sched, bool ALIGN_EPI, int LMASK = -1, int LMASKB = LMASK>
; __device__ __forceinline__ void gemm_phase(PG8_LAS unsigned char* lds, const Gemm g, const Sched& S, const Epi& E) {
;     ...
;             PG8_WAIT_V(8); PG8_WAIT_L(0); PG8_BAR; PG8_MMA(1, 0, At, B0); PG8_MMA(1, 1, At, B1); PG8_BAR; PG8_SCHED;
;             PG8_LDB(B0, 1, 0); PG8_LDB(B1, 1, 1); PG8_SCHED; PG8_LDA(At, 1, 0); PG8_STAGE(PG8_SA(0, 1), a2 + hstepA, voffA);
;             PG8_WAIT_V(8); PG8_WAIT_L(0); PG8_BAR; PG8_MMA(0, 0, At, B0); PG8_MMA(0, 1, At, B1); PG8_BAR; PG8_SCHED;
	s_setprio 1
	v_mfma_f32_16x16x32_bf16 v[62:65], v[138:141], v[174:177], v[62:65]
	v_mfma_f32_16x16x32_bf16 v[58:61], v[150:153], v[174:177], v[58:61]
	v_mfma_f32_16x16x32_bf16 v[46:49], v[138:141], v[206:209], v[46:49]
	v_mfma_f32_16x16x32_bf16 v[42:45], v[150:153], v[206:209], v[42:45]
	v_mfma_f32_16x16x32_bf16 v[30:33], v[138:141], v[222:225], v[30:33]
	v_mfma_f32_16x16x32_bf16 v[26:29], v[150:153], v[222:225], v[26:29]
	v_mfma_f32_16x16x32_bf16 v[14:17], v[138:141], v[230:233], v[14:17]
	v_mfma_f32_16x16x32_bf16 v[10:13], v[150:153], v[230:233], v[10:13]
	v_mfma_f32_16x16x32_bf16 v[62:65], v[146:149], v[188:191], v[62:65]
	v_mfma_f32_16x16x32_bf16 v[58:61], v[154:157], v[188:191], v[58:61]
	v_mfma_f32_16x16x32_bf16 v[46:49], v[146:149], v[218:221], v[46:49]
	v_mfma_f32_16x16x32_bf16 v[42:45], v[154:157], v[218:221], v[42:45]
	v_mfma_f32_16x16x32_bf16 v[30:33], v[146:149], v[226:229], v[30:33]
	v_mfma_f32_16x16x32_bf16 v[26:29], v[154:157], v[226:229], v[26:29]
	v_mfma_f32_16x16x32_bf16 v[14:17], v[146:149], v[234:237], v[14:17]
	v_mfma_f32_16x16x32_bf16 v[10:13], v[154:157], v[234:237], v[10:13]
	s_setprio 0
	s_setprio 1
	v_mfma_f32_16x16x32_bf16 v[54:57], v[158:161], v[174:177], v[54:57]
	v_mfma_f32_16x16x32_bf16 v[50:53], v[166:169], v[174:177], v[50:53]
	v_mfma_f32_16x16x32_bf16 v[38:41], v[158:161], v[206:209], v[38:41]
	v_mfma_f32_16x16x32_bf16 v[34:37], v[166:169], v[206:209], v[34:37]
	v_mfma_f32_16x16x32_bf16 v[22:25], v[158:161], v[222:225], v[22:25]
	v_mfma_f32_16x16x32_bf16 v[18:21], v[166:169], v[222:225], v[18:21]
	v_mfma_f32_16x16x32_bf16 v[6:9], v[158:161], v[230:233], v[6:9]
	v_mfma_f32_16x16x32_bf16 v[2:5], v[166:169], v[230:233], v[2:5]
	v_mfma_f32_16x16x32_bf16 v[54:57], v[162:165], v[188:191], v[54:57]
	v_mfma_f32_16x16x32_bf16 v[50:53], v[170:173], v[188:191], v[50:53]
	v_mfma_f32_16x16x32_bf16 v[38:41], v[162:165], v[218:221], v[38:41]
	v_mfma_f32_16x16x32_bf16 v[34:37], v[170:173], v[218:221], v[34:37]
	v_mfma_f32_16x16x32_bf16 v[22:25], v[162:165], v[226:229], v[22:25]
	v_mfma_f32_16x16x32_bf16 v[18:21], v[170:173], v[226:229], v[18:21]
	v_mfma_f32_16x16x32_bf16 v[6:9], v[162:165], v[234:237], v[6:9]
	v_mfma_f32_16x16x32_bf16 v[2:5], v[170:173], v[234:237], v[2:5]
	s_setprio 0
	s_barrier
	s_add_i32 s50, 0, 0x18000
	s_add_i32 s51, 0, 0x1c000
	v_add_u32_e32 v154, s50, v143
	v_add_u32_e32 v170, s51, v143
	ds_read_b128 v[138:141], v154
	ds_read_b128 v[146:149], v154 offset:1024
	ds_read_b128 v[150:153], v154 offset:2048
	ds_read_b128 v[154:157], v154 offset:3072
	ds_read_b128 v[158:161], v170
	ds_read_b128 v[162:165], v170 offset:1024
	ds_read_b128 v[166:169], v170 offset:2048
	ds_read_b128 v[170:173], v170 offset:3072
	s_add_u32 s28, s28, 0x100000
	s_addc_u32 s29, s29, 0
	s_mov_b32 m0, s40
	v_lshl_add_u64 v[240:241], s[28:29], 0, v[130:131]
	ds_read_b128 v[174:177], v145 offset:32768
	ds_read_b128 v[188:191], v145 offset:33792
	ds_read_b128 v[206:209], v145 offset:34816
	ds_read_b128 v[218:221], v145 offset:35840
	ds_read_b128 v[222:225], v145 offset:36864
	ds_read_b128 v[226:229], v145 offset:37888
	ds_read_b128 v[230:233], v145 offset:38912
	ds_read_b128 v[234:237], v145 offset:39936
	global_load_lds_dwordx4 v[240:241], off
	v_lshl_add_u64 v[240:241], s[28:29], 0, v[132:133]
	s_mov_b32 m0, s41
	s_nop 0
	global_load_lds_dwordx4 v[240:241], off
	s_waitcnt vmcnt(8)
	s_waitcnt lgkmcnt(0)
	s_barrier
	s_setprio 1
	v_mfma_f32_16x16x32_bf16 v[126:129], v[138:141], v[174:177], v[126:129]
	v_mfma_f32_16x16x32_bf16 v[122:125], v[150:153], v[174:177], v[122:125]
	v_mfma_f32_16x16x32_bf16 v[110:113], v[138:141], v[206:209], v[110:113]
	v_mfma_f32_16x16x32_bf16 v[106:109], v[150:153], v[206:209], v[106:109]
	v_mfma_f32_16x16x32_bf16 v[94:97], v[138:141], v[222:225], v[94:97]
	v_mfma_f32_16x16x32_bf16 v[90:93], v[150:153], v[222:225], v[90:93]
	v_mfma_f32_16x16x32_bf16 v[78:81], v[138:141], v[230:233], v[78:81]
	v_mfma_f32_16x16x32_bf16 v[74:77], v[150:153], v[230:233], v[74:77]
	v_mfma_f32_16x16x32_bf16 v[126:129], v[146:149], v[188:191], v[126:129]
	v_mfma_f32_16x16x32_bf16 v[122:125], v[154:157], v[188:191], v[122:125]
	v_mfma_f32_16x16x32_bf16 v[110:113], v[146:149], v[218:221], v[110:113]
	v_mfma_f32_16x16x32_bf16 v[106:109], v[154:157], v[218:221], v[106:109]
	v_mfma_f32_16x16x32_bf16 v[94:97], v[146:149], v[226:229], v[94:97]
	v_mfma_f32_16x16x32_bf16 v[90:93], v[154:157], v[226:229], v[90:93]
	v_mfma_f32_16x16x32_bf16 v[78:81], v[146:149], v[234:237], v[78:81]
	v_mfma_f32_16x16x32_bf16 v[74:77], v[154:157], v[234:237], v[74:77]
	s_setprio 0
	s_setprio 1
	v_mfma_f32_16x16x32_bf16 v[118:121], v[158:161], v[174:177], v[118:121]
	v_mfma_f32_16x16x32_bf16 v[114:117], v[166:169], v[174:177], v[114:117]
	v_mfma_f32_16x16x32_bf16 v[102:105], v[158:161], v[206:209], v[102:105]
	v_mfma_f32_16x16x32_bf16 v[98:101], v[166:169], v[206:209], v[98:101]
	v_mfma_f32_16x16x32_bf16 v[86:89], v[158:161], v[222:225], v[86:89]
	v_mfma_f32_16x16x32_bf16 v[82:85], v[166:169], v[222:225], v[82:85]
	v_mfma_f32_16x16x32_bf16 v[70:73], v[158:161], v[230:233], v[70:73]
	v_mfma_f32_16x16x32_bf16 v[66:69], v[166:169], v[230:233], v[66:69]
	v_mfma_f32_16x16x32_bf16 v[118:121], v[162:165], v[188:191], v[118:121]
	v_mfma_f32_16x16x32_bf16 v[114:117], v[170:173], v[188:191], v[114:117]
	v_mfma_f32_16x16x32_bf16 v[102:105], v[162:165], v[218:221], v[102:105]
	v_mfma_f32_16x16x32_bf16 v[98:101], v[170:173], v[218:221], v[98:101]
	v_mfma_f32_16x16x32_bf16 v[86:89], v[162:165], v[226:229], v[86:89]
	v_mfma_f32_16x16x32_bf16 v[82:85], v[170:173], v[226:229], v[82:85]
	v_mfma_f32_16x16x32_bf16 v[70:73], v[162:165], v[234:237], v[70:73]
	v_mfma_f32_16x16x32_bf16 v[66:69], v[170:173], v[234:237], v[66:69]
	s_setprio 0
	s_barrier
; #define PG8_STAGE(bufoff, gbase, voff) do { _Pragma("unroll") for (int _i = 0; _i < 2; ++_i) \
;         __builtin_amdgcn_global_load_lds((const unsigned*)((const char*)(gbase) + (voff)[_i]), (PG8_LAS unsigned*)(lds + (bufoff) + ldsw + _i * 8192), 16, 0, 0); } while (0)
; #define PG8_LDA(dst, b, h) do { _Pragma("unroll") for (int m = 0; m < 4; ++m) _Pragma("unroll") for (int k = 0; k < 2; ++k) dst[m][k] = *(const PG8_LAS bf16x8*)(lds + PG8_SA(b, h) + aoff + m * 2048 + k * 1024); } while (0)
; #define PG8_MMA(ai, bj, At, Bt) do { __builtin_amdgcn_s_setprio(1); _Pragma("unroll") for (int m = 0; m < 4; ++m) _Pragma("unroll") for (int n = 0; n < 2; ++n) _Pragma("unroll") for (int k = 0; k < 2; ++k) \
;         acc[ai][bj][m][n] = __builtin_amdgcn_mfma_f32_16x16x32_bf16(Bt[n][k], At[m][k], acc[ai][bj][m][n], 0, 0, 0); __builtin_amdgcn_s_setprio(0); } while (0)
; #define PG8_WAIT_V(n) asm volatile("s_waitcnt vmcnt(" #n ")" ::: "memory")
; #define PG8_WAIT_L(n) asm volatile("s_waitcnt lgkmcnt(" #n ")" ::: "memory")
; #define PG8_BAR __builtin_amdgcn_s_barrier()
; #define PG8_SCHED __builtin_amdgcn_sched_barrier(0)
; template <class Epi, class Sched, bool ALIGN_EPI, int LMASK = -1, int LMASKB = LMASK>
; __device__ __forceinline__ void gemm_phase(PG8_LAS unsigned char* lds, const Gemm g, const Sched& S, const Epi& E) {
;     ...
;             PG8_LDA(At, 1, 1); PG8_STAGE(PG8_SB(1, 0), b3, voffB); PG8_STAGE(PG8_SB(1, 1), b3 + hstepB, voffB); PG8_STAGE(PG8_SA(1, 0), a3, voffA);
;             PG8_WAIT_V(8); PG8_WAIT_L(0); PG8_BAR; PG8_MMA(1, 0, At, B0); PG8_MMA(1, 1, At, B1); PG8_BAR; PG8_SCHED;
;         }
;         if constexpr (ALIGN_EPI) { if (wr == 0) PG8_BAR; }
;         E(acc, cur, wr, wc, fr, fq);
;         if (!has_next) break;
	s_add_i32 s28, s50, s38
	v_lshl_add_u64 v[194:195], v[194:195], 0, s[80:81]
	s_mov_b32 m0, s28
	ds_read_b128 v[174:177], v145 offset:49152
	ds_read_b128 v[188:191], v145 offset:50176
	ds_read_b128 v[206:209], v145 offset:51200
	ds_read_b128 v[218:221], v145 offset:52224
	ds_read_b128 v[222:225], v145 offset:53248
	ds_read_b128 v[226:229], v145 offset:54272
	ds_read_b128 v[230:233], v145 offset:55296
	ds_read_b128 v[234:237], v145 offset:56320
	global_load_lds_dwordx4 v[194:195], off
	s_add_i32 m0, s28, 0x2000
	s_add_u32 s26, s26, 0x100800
	v_lshl_add_u64 v[194:195], v[210:211], 0, s[80:81]
	s_addc_u32 s27, s27, 0
	s_add_i32 s28, s51, s38
	global_load_lds_dwordx4 v[194:195], off
	v_lshl_add_u64 v[194:195], s[26:27], 0, v[130:131]
	s_mov_b32 m0, s28
	s_nop 0
	global_load_lds_dwordx4 v[194:195], off
	v_lshl_add_u64 v[194:195], s[26:27], 0, v[132:133]
	s_add_i32 m0, s28, 0x2000
	s_nop 0
	global_load_lds_dwordx4 v[194:195], off
	v_lshl_add_u64 v[194:195], v[212:213], 0, s[80:81]
	s_mov_b32 m0, s42
	s_nop 0
	global_load_lds_dwordx4 v[194:195], off
	v_lshl_add_u64 v[194:195], v[238:239], 0, s[80:81]
	s_mov_b32 m0, s43
	s_nop 0
	global_load_lds_dwordx4 v[194:195], off
	s_waitcnt vmcnt(8)
	s_waitcnt lgkmcnt(0)
	s_barrier
	s_setprio 1
	v_mfma_f32_16x16x32_bf16 v[62:65], v[138:141], v[174:177], v[62:65]
	v_mfma_f32_16x16x32_bf16 v[58:61], v[150:153], v[174:177], v[58:61]
	v_mfma_f32_16x16x32_bf16 v[46:49], v[138:141], v[206:209], v[46:49]
	v_mfma_f32_16x16x32_bf16 v[42:45], v[150:153], v[206:209], v[42:45]
	v_mfma_f32_16x16x32_bf16 v[30:33], v[138:141], v[222:225], v[30:33]
	v_mfma_f32_16x16x32_bf16 v[26:29], v[150:153], v[222:225], v[26:29]
	v_mfma_f32_16x16x32_bf16 v[14:17], v[138:141], v[230:233], v[14:17]
	v_mfma_f32_16x16x32_bf16 v[10:13], v[150:153], v[230:233], v[10:13]
	v_mfma_f32_16x16x32_bf16 v[62:65], v[146:149], v[188:191], v[62:65]
	v_mfma_f32_16x16x32_bf16 v[58:61], v[154:157], v[188:191], v[58:61]
	v_mfma_f32_16x16x32_bf16 v[46:49], v[146:149], v[218:221], v[46:49]
	v_mfma_f32_16x16x32_bf16 v[42:45], v[154:157], v[218:221], v[42:45]
	v_mfma_f32_16x16x32_bf16 v[30:33], v[146:149], v[226:229], v[30:33]
	v_mfma_f32_16x16x32_bf16 v[26:29], v[154:157], v[226:229], v[26:29]
	v_mfma_f32_16x16x32_bf16 v[14:17], v[146:149], v[234:237], v[14:17]
	v_mfma_f32_16x16x32_bf16 v[10:13], v[154:157], v[234:237], v[10:13]
	s_setprio 0
	s_setprio 1
	v_mfma_f32_16x16x32_bf16 v[54:57], v[158:161], v[174:177], v[54:57]
	v_mfma_f32_16x16x32_bf16 v[50:53], v[166:169], v[174:177], v[50:53]
	v_mfma_f32_16x16x32_bf16 v[38:41], v[158:161], v[206:209], v[38:41]
	v_mfma_f32_16x16x32_bf16 v[34:37], v[166:169], v[206:209], v[34:37]
	v_mfma_f32_16x16x32_bf16 v[22:25], v[158:161], v[222:225], v[22:25]
	v_mfma_f32_16x16x32_bf16 v[18:21], v[166:169], v[222:225], v[18:21]
	v_mfma_f32_16x16x32_bf16 v[6:9], v[158:161], v[230:233], v[6:9]
	v_mfma_f32_16x16x32_bf16 v[2:5], v[166:169], v[230:233], v[2:5]
	v_mfma_f32_16x16x32_bf16 v[54:57], v[162:165], v[188:191], v[54:57]
	v_mfma_f32_16x16x32_bf16 v[50:53], v[170:173], v[188:191], v[50:53]
	v_mfma_f32_16x16x32_bf16 v[38:41], v[162:165], v[218:221], v[38:41]
	v_mfma_f32_16x16x32_bf16 v[34:37], v[170:173], v[218:221], v[34:37]
	v_mfma_f32_16x16x32_bf16 v[22:25], v[162:165], v[226:229], v[22:25]
	v_mfma_f32_16x16x32_bf16 v[18:21], v[170:173], v[226:229], v[18:21]
	v_mfma_f32_16x16x32_bf16 v[6:9], v[162:165], v[234:237], v[6:9]
	v_mfma_f32_16x16x32_bf16 v[2:5], v[170:173], v[234:237], v[2:5]
	s_setprio 0
	s_barrier
	s_add_i32 s49, s49, 2
	s_add_u32 s24, s24, 0x1000
	s_addc_u32 s25, s25, 0
	s_add_u32 s47, s47, 0x1000
	s_addc_u32 s48, s48, 0
	s_cmp_gt_u32 s49, 61
	s_cbranch_scc0 .LBB0_678
	s_and_b64 vcc, exec, s[12:13]
	s_cbranch_vccz .LBB0_681
	s_barrier

; #define PG8_STAGE(bufoff, gbase, voff) do { _Pragma("unroll") for (int _i = 0; _i < 2; ++_i) \
;         __builtin_amdgcn_global_load_lds((const unsigned*)((const char*)(gbase) + (voff)[_i]), (PG8_LAS unsigned*)(lds + (bufoff) + ldsw + _i * 8192), 16, 0, 0); } while (0)
; #define PG8_LDA(dst, b, h) do { _Pragma("unroll") for (int m = 0; m < 4; ++m) _Pragma("unroll") for (int k = 0; k < 2; ++k) dst[m][k] = *(const PG8_LAS bf16x8*)(lds + PG8_SA(b, h) + aoff + m * 2048 + k * 1024); } while (0)
; #define PG8_LDB(dst, b, h) do { _Pragma("unroll") for (int n = 0; n < 2; ++n) _Pragma("unroll") for (int k = 0; k < 2; ++k) dst[n][k] = *(const PG8_LAS bf16x8*)(lds + PG8_SB(b, h) + boff + n * 2048 + k * 1024); } while (0)
; #define PG8_MMA(ai, bj, At, Bt) do { __builtin_amdgcn_s_setprio(1); _Pragma("unroll") for (int m = 0; m < 4; ++m) _Pragma("unroll") for (int n = 0; n < 2; ++n) _Pragma("unroll") for (int k = 0; k < 2; ++k) \
;         acc[ai][bj][m][n] = __builtin_amdgcn_mfma_f32_16x16x32_bf16(Bt[n][k], At[m][k], acc[ai][bj][m][n], 0, 0, 0); __builtin_amdgcn_s_setprio(0); } while (0)
; #define PG8_WAIT_V(n) asm volatile("s_waitcnt vmcnt(" #n ")" ::: "memory")
; #define PG8_WAIT_L(n) asm volatile("s_waitcnt lgkmcnt(" #n ")" ::: "memory")
; #define PG8_BAR __builtin_amdgcn_s_barrier()
; #define PG8_SCHED __builtin_amdgcn_sched_barrier(0)
; template <class Epi, class Sched, bool ALIGN_EPI, int LMASK = -1, int LMASKB = LMASK>
; __device__ __forceinline__ void gemm_phase(PG8_LAS unsigned char* lds, const Gemm g, const Sched& S, const Epi& E) {
;     ...
;             const bool last = (t == nt - 2);
;             const char* a1 = cA + (size_t)(t + 1) * kstepA;
;             const char* a2 = last ? nA : cA + (size_t)(t + 2) * kstepA; const char* b2 = last ? nB : cB + (size_t)(t + 2) * kstepB;
;             const char* a3 = a2 + kstepA; const char* b3 = b2 + kstepB;
;             PG8_LDB(B0, 0, 0); PG8_LDB(B1, 0, 1); PG8_SCHED; PG8_LDA(At, 0, 0); PG8_STAGE(PG8_SA(1, 1), a1 + hstepA, voffA);
;             PG8_WAIT_V(8); PG8_WAIT_L(0); PG8_BAR; PG8_MMA(0, 0, At, B0); PG8_MMA(0, 1, At, B1); PG8_BAR; PG8_SCHED;
;             PG8_LDA(At, 0, 1); PG8_STAGE(PG8_SB(0, 0), b2, voffB); PG8_STAGE(PG8_SB(0, 1), b2 + hstepB, voffB); PG8_STAGE(PG8_SA(0, 0), a2, voffA);
.LBB0_761:
	s_add_u32 s2, s28, 0xffc00800
	s_addc_u32 s3, s29, -1
	s_add_i32 s51, 0, 0x10000
	s_cmpk_eq_i32 s50, 0xfc
	s_cselect_b32 s31, s19, s3
	s_cselect_b32 s30, s46, s2
	v_add_u32_e32 v146, s51, v149
	s_cselect_b32 s3, s17, s49
	s_cselect_b32 s2, s47, s48
	s_add_i32 s54, 0, 0x14000
	ds_read_b128 v[130:133], v146
	ds_read_b128 v[142:145], v146 offset:1024
	ds_read_b128 v[152:155], v146 offset:2048
	ds_read_b128 v[156:159], v146 offset:3072
	v_add_u32_e32 v146, s54, v149
	ds_read_b128 v[160:163], v146
	ds_read_b128 v[164:167], v146 offset:1024
	ds_read_b128 v[168:171], v146 offset:2048
	ds_read_b128 v[172:175], v146 offset:3072
	v_lshl_add_u64 v[146:147], s[28:29], 0, v[138:139]
	s_add_i32 m0, s25, 0xc000
	ds_read_b128 v[188:191], v151
	ds_read_b128 v[206:209], v151 offset:1024
	ds_read_b128 v[218:221], v151 offset:2048
	ds_read_b128 v[222:225], v151 offset:3072
	ds_read_b128 v[226:229], v151 offset:4096
	ds_read_b128 v[230:233], v151 offset:5120
	ds_read_b128 v[234:237], v151 offset:6144
	ds_read_b128 v[238:241], v151 offset:7168
	global_load_lds_dwordx4 v[146:147], off
	v_lshl_add_u64 v[146:147], s[28:29], 0, v[140:141]
	s_add_i32 m0, s25, 0xe000
	s_nop 0
	global_load_lds_dwordx4 v[146:147], off
	s_waitcnt vmcnt(8)
	s_waitcnt lgkmcnt(0)
	s_barrier
	s_setprio 1
	v_mfma_f32_16x16x32_bf16 v[126:129], v[130:133], v[188:191], v[126:129]
	v_mfma_f32_16x16x32_bf16 v[122:125], v[152:155], v[188:191], v[122:125]
	v_mfma_f32_16x16x32_bf16 v[110:113], v[130:133], v[218:221], v[110:113]
	v_mfma_f32_16x16x32_bf16 v[106:109], v[152:155], v[218:221], v[106:109]
	v_mfma_f32_16x16x32_bf16 v[94:97], v[130:133], v[226:229], v[94:97]
	v_mfma_f32_16x16x32_bf16 v[90:93], v[152:155], v[226:229], v[90:93]
	v_mfma_f32_16x16x32_bf16 v[78:81], v[130:133], v[234:237], v[78:81]
	v_mfma_f32_16x16x32_bf16 v[74:77], v[152:155], v[234:237], v[74:77]
	v_mfma_f32_16x16x32_bf16 v[126:129], v[142:145], v[206:209], v[126:129]
	v_mfma_f32_16x16x32_bf16 v[122:125], v[156:159], v[206:209], v[122:125]
	v_mfma_f32_16x16x32_bf16 v[110:113], v[142:145], v[222:225], v[110:113]
	v_mfma_f32_16x16x32_bf16 v[106:109], v[156:159], v[222:225], v[106:109]
	v_mfma_f32_16x16x32_bf16 v[94:97], v[142:145], v[230:233], v[94:97]
	v_mfma_f32_16x16x32_bf16 v[90:93], v[156:159], v[230:233], v[90:93]
	v_mfma_f32_16x16x32_bf16 v[78:81], v[142:145], v[238:241], v[78:81]
	v_mfma_f32_16x16x32_bf16 v[74:77], v[156:159], v[238:241], v[74:77]
	s_setprio 0
	s_setprio 1
	v_mfma_f32_16x16x32_bf16 v[118:121], v[160:163], v[188:191], v[118:121]
	v_mfma_f32_16x16x32_bf16 v[114:117], v[168:171], v[188:191], v[114:117]
	v_mfma_f32_16x16x32_bf16 v[102:105], v[160:163], v[218:221], v[102:105]
	v_mfma_f32_16x16x32_bf16 v[98:101], v[168:171], v[218:221], v[98:101]
	v_mfma_f32_16x16x32_bf16 v[86:89], v[160:163], v[226:229], v[86:89]
	v_mfma_f32_16x16x32_bf16 v[82:85], v[168:171], v[226:229], v[82:85]
	v_mfma_f32_16x16x32_bf16 v[70:73], v[160:163], v[234:237], v[70:73]
	v_mfma_f32_16x16x32_bf16 v[66:69], v[168:171], v[234:237], v[66:69]
	v_mfma_f32_16x16x32_bf16 v[118:121], v[164:167], v[206:209], v[118:121]
	v_mfma_f32_16x16x32_bf16 v[114:117], v[172:175], v[206:209], v[114:117]
	v_mfma_f32_16x16x32_bf16 v[102:105], v[164:167], v[222:225], v[102:105]
	v_mfma_f32_16x16x32_bf16 v[98:101], v[172:175], v[222:225], v[98:101]
	v_mfma_f32_16x16x32_bf16 v[86:89], v[164:167], v[230:233], v[86:89]
	v_mfma_f32_16x16x32_bf16 v[82:85], v[172:175], v[230:233], v[82:85]
	v_mfma_f32_16x16x32_bf16 v[70:73], v[164:167], v[238:241], v[70:73]
	v_mfma_f32_16x16x32_bf16 v[66:69], v[172:175], v[238:241], v[66:69]
	s_setprio 0
	s_barrier
	s_add_i32 s51, s51, s38
	v_lshl_add_u64 v[146:147], s[2:3], 0, v[134:135]
	s_mov_b32 m0, s51
	ds_read_b128 v[188:191], v151 offset:16384
	ds_read_b128 v[206:209], v151 offset:17408
	ds_read_b128 v[218:221], v151 offset:18432
	ds_read_b128 v[222:225], v151 offset:19456
	ds_read_b128 v[226:229], v151 offset:20480
	ds_read_b128 v[230:233], v151 offset:21504
	ds_read_b128 v[234:237], v151 offset:22528
	ds_read_b128 v[238:241], v151 offset:23552
	global_load_lds_dwordx4 v[146:147], off
	s_add_i32 m0, s51, 0x2000
	s_add_u32 s52, s2, 0x400000
	v_lshl_add_u64 v[176:177], s[2:3], 0, v[136:137]
	s_addc_u32 s53, s3, 0
	s_add_i32 s51, s54, s38
	global_load_lds_dwordx4 v[176:177], off
	v_lshl_add_u64 v[194:195], s[52:53], 0, v[134:135]
	s_mov_b32 m0, s51
	v_lshl_add_u64 v[210:211], s[30:31], 0, v[136:137]
	global_load_lds_dwordx4 v[194:195], off
	v_lshl_add_u64 v[194:195], s[52:53], 0, v[136:137]
	s_add_i32 m0, s51, 0x2000
	s_nop 0
	global_load_lds_dwordx4 v[194:195], off
	v_lshl_add_u64 v[194:195], s[30:31], 0, v[134:135]
	s_mov_b32 m0, s25
	s_nop 0
	global_load_lds_dwordx4 v[194:195], off
	s_mov_b32 m0, s27
	s_nop 0
	global_load_lds_dwordx4 v[210:211], off
	s_waitcnt vmcnt(8)
	s_waitcnt lgkmcnt(0)
	s_barrier
; #define PG8_STAGE(bufoff, gbase, voff) do { _Pragma("unroll") for (int _i = 0; _i < 2; ++_i) \
;         __builtin_amdgcn_global_load_lds((const unsigned*)((const char*)(gbase) + (voff)[_i]), (PG8_LAS unsigned*)(lds + (bufoff) + ldsw + _i * 8192), 16, 0, 0); } while (0)
; #define PG8_LDA(dst, b, h) do { _Pragma("unroll") for (int m = 0; m < 4; ++m) _Pragma("unroll") for (int k = 0; k < 2; ++k) dst[m][k] = *(const PG8_LAS bf16x8*)(lds + PG8_SA(b, h) + aoff + m * 2048 + k * 1024); } while (0)
; #define PG8_LDB(dst, b, h) do { _Pragma("unroll") for (int n = 0; n < 2; ++n) _Pragma("unroll") for (int k = 0; k < 2; ++k) dst[n][k] = *(const PG8_LAS bf16x8*)(lds + PG8_SB(b, h) + boff + n * 2048 + k * 1024); } while (0)
; #define PG8_MMA(ai, bj, At, Bt) do { __builtin_amdgcn_s_setprio(1); _Pragma("unroll") for (int m = 0; m < 4; ++m) _Pragma("unroll") for (int n = 0; n < 2; ++n) _Pragma("unroll") for (int k = 0; k < 2; ++k) \
;         acc[ai][bj][m][n] = __builtin_amdgcn_mfma_f32_16x16x32_bf16(Bt[n][k], At[m][k], acc[ai][bj][m][n], 0, 0, 0); __builtin_amdgcn_s_setprio(0); } while (0)
; #define PG8_WAIT_V(n) asm volatile("s_waitcnt vmcnt(" #n ")" ::: "memory")
; #define PG8_WAIT_L(n) asm volatile("s_waitcnt lgkmcnt(" #n ")" ::: "memory")
; #define PG8_BAR __builtin_amdgcn_s_barrier()
; #define PG8_SCHED __builtin_amdgcn_sched_barrier(0)
; template <class Epi, class Sched, bool ALIGN_EPI, int LMASK = -1, int LMASKB = LMASK>
; __device__ __forceinline__ void gemm_phase(PG8_LAS unsigned char* lds, const Gemm g, const Sched& S, const Epi& E) {
;     ...
;             PG8_WAIT_V(8); PG8_WAIT_L(0); PG8_BAR; PG8_MMA(1, 0, At, B0); PG8_MMA(1, 1, At, B1); PG8_BAR; PG8_SCHED;
;             PG8_LDB(B0, 1, 0); PG8_LDB(B1, 1, 1); PG8_SCHED; PG8_LDA(At, 1, 0); PG8_STAGE(PG8_SA(0, 1), a2 + hstepA, voffA);
;             PG8_WAIT_V(8); PG8_WAIT_L(0); PG8_BAR; PG8_MMA(0, 0, At, B0); PG8_MMA(0, 1, At, B1); PG8_BAR; PG8_SCHED;
	s_setprio 1
	v_mfma_f32_16x16x32_bf16 v[62:65], v[130:133], v[188:191], v[62:65]
	v_mfma_f32_16x16x32_bf16 v[58:61], v[152:155], v[188:191], v[58:61]
	v_mfma_f32_16x16x32_bf16 v[46:49], v[130:133], v[218:221], v[46:49]
	v_mfma_f32_16x16x32_bf16 v[42:45], v[152:155], v[218:221], v[42:45]
	v_mfma_f32_16x16x32_bf16 v[30:33], v[130:133], v[226:229], v[30:33]
	v_mfma_f32_16x16x32_bf16 v[26:29], v[152:155], v[226:229], v[26:29]
	v_mfma_f32_16x16x32_bf16 v[14:17], v[130:133], v[234:237], v[14:17]
	v_mfma_f32_16x16x32_bf16 v[10:13], v[152:155], v[234:237], v[10:13]
	v_mfma_f32_16x16x32_bf16 v[62:65], v[142:145], v[206:209], v[62:65]
	v_mfma_f32_16x16x32_bf16 v[58:61], v[156:159], v[206:209], v[58:61]
	v_mfma_f32_16x16x32_bf16 v[46:49], v[142:145], v[222:225], v[46:49]
	v_mfma_f32_16x16x32_bf16 v[42:45], v[156:159], v[222:225], v[42:45]
	v_mfma_f32_16x16x32_bf16 v[30:33], v[142:145], v[230:233], v[30:33]
	v_mfma_f32_16x16x32_bf16 v[26:29], v[156:159], v[230:233], v[26:29]
	v_mfma_f32_16x16x32_bf16 v[14:17], v[142:145], v[238:241], v[14:17]
	v_mfma_f32_16x16x32_bf16 v[10:13], v[156:159], v[238:241], v[10:13]
	s_setprio 0
	s_setprio 1
	v_mfma_f32_16x16x32_bf16 v[54:57], v[160:163], v[188:191], v[54:57]
	v_mfma_f32_16x16x32_bf16 v[50:53], v[168:171], v[188:191], v[50:53]
	v_mfma_f32_16x16x32_bf16 v[38:41], v[160:163], v[218:221], v[38:41]
	v_mfma_f32_16x16x32_bf16 v[34:37], v[168:171], v[218:221], v[34:37]
	v_mfma_f32_16x16x32_bf16 v[22:25], v[160:163], v[226:229], v[22:25]
	v_mfma_f32_16x16x32_bf16 v[18:21], v[168:171], v[226:229], v[18:21]
	v_mfma_f32_16x16x32_bf16 v[6:9], v[160:163], v[234:237], v[6:9]
	v_mfma_f32_16x16x32_bf16 v[2:5], v[168:171], v[234:237], v[2:5]
	v_mfma_f32_16x16x32_bf16 v[54:57], v[164:167], v[206:209], v[54:57]
	v_mfma_f32_16x16x32_bf16 v[50:53], v[172:175], v[206:209], v[50:53]
	v_mfma_f32_16x16x32_bf16 v[38:41], v[164:167], v[222:225], v[38:41]
	v_mfma_f32_16x16x32_bf16 v[34:37], v[172:175], v[222:225], v[34:37]
	v_mfma_f32_16x16x32_bf16 v[22:25], v[164:167], v[230:233], v[22:25]
	v_mfma_f32_16x16x32_bf16 v[18:21], v[172:175], v[230:233], v[18:21]
	v_mfma_f32_16x16x32_bf16 v[6:9], v[164:167], v[238:241], v[6:9]
	v_mfma_f32_16x16x32_bf16 v[2:5], v[172:175], v[238:241], v[2:5]
	s_setprio 0
	s_barrier
	s_add_i32 s51, 0, 0x18000
	s_add_i32 s52, 0, 0x1c000
	v_add_u32_e32 v156, s51, v149
	v_add_u32_e32 v172, s52, v149
	ds_read_b128 v[130:133], v156
	ds_read_b128 v[142:145], v156 offset:1024
	ds_read_b128 v[152:155], v156 offset:2048
	ds_read_b128 v[156:159], v156 offset:3072
	ds_read_b128 v[160:163], v172
	ds_read_b128 v[164:167], v172 offset:1024
	ds_read_b128 v[168:171], v172 offset:2048
	ds_read_b128 v[172:175], v172 offset:3072
	s_add_u32 s30, s30, 0x400000
	s_addc_u32 s31, s31, 0
	s_mov_b32 m0, s39
	v_lshl_add_u64 v[212:213], s[30:31], 0, v[134:135]
	ds_read_b128 v[188:191], v151 offset:32768
	ds_read_b128 v[206:209], v151 offset:33792
	ds_read_b128 v[218:221], v151 offset:34816
	ds_read_b128 v[222:225], v151 offset:35840
	ds_read_b128 v[226:229], v151 offset:36864
	ds_read_b128 v[230:233], v151 offset:37888
	ds_read_b128 v[234:237], v151 offset:38912
	ds_read_b128 v[238:241], v151 offset:39936
	global_load_lds_dwordx4 v[212:213], off
	v_lshl_add_u64 v[212:213], s[30:31], 0, v[136:137]
	s_mov_b32 m0, s40
	s_nop 0
	global_load_lds_dwordx4 v[212:213], off
	s_waitcnt vmcnt(8)
	s_waitcnt lgkmcnt(0)
	s_barrier
	s_setprio 1
	v_mfma_f32_16x16x32_bf16 v[126:129], v[130:133], v[188:191], v[126:129]
	v_mfma_f32_16x16x32_bf16 v[122:125], v[152:155], v[188:191], v[122:125]
	v_mfma_f32_16x16x32_bf16 v[110:113], v[130:133], v[218:221], v[110:113]
	v_mfma_f32_16x16x32_bf16 v[106:109], v[152:155], v[218:221], v[106:109]
	v_mfma_f32_16x16x32_bf16 v[94:97], v[130:133], v[226:229], v[94:97]
	v_mfma_f32_16x16x32_bf16 v[90:93], v[152:155], v[226:229], v[90:93]
	v_mfma_f32_16x16x32_bf16 v[78:81], v[130:133], v[234:237], v[78:81]
	v_mfma_f32_16x16x32_bf16 v[74:77], v[152:155], v[234:237], v[74:77]
	v_mfma_f32_16x16x32_bf16 v[126:129], v[142:145], v[206:209], v[126:129]
	v_mfma_f32_16x16x32_bf16 v[122:125], v[156:159], v[206:209], v[122:125]
	v_mfma_f32_16x16x32_bf16 v[110:113], v[142:145], v[222:225], v[110:113]
	v_mfma_f32_16x16x32_bf16 v[106:109], v[156:159], v[222:225], v[106:109]
	v_mfma_f32_16x16x32_bf16 v[94:97], v[142:145], v[230:233], v[94:97]
	v_mfma_f32_16x16x32_bf16 v[90:93], v[156:159], v[230:233], v[90:93]
	v_mfma_f32_16x16x32_bf16 v[78:81], v[142:145], v[238:241], v[78:81]
	v_mfma_f32_16x16x32_bf16 v[74:77], v[156:159], v[238:241], v[74:77]
	s_setprio 0
	s_setprio 1
	v_mfma_f32_16x16x32_bf16 v[118:121], v[160:163], v[188:191], v[118:121]
	v_mfma_f32_16x16x32_bf16 v[114:117], v[168:171], v[188:191], v[114:117]
	v_mfma_f32_16x16x32_bf16 v[102:105], v[160:163], v[218:221], v[102:105]
	v_mfma_f32_16x16x32_bf16 v[98:101], v[168:171], v[218:221], v[98:101]
	v_mfma_f32_16x16x32_bf16 v[86:89], v[160:163], v[226:229], v[86:89]
	v_mfma_f32_16x16x32_bf16 v[82:85], v[168:171], v[226:229], v[82:85]
	v_mfma_f32_16x16x32_bf16 v[70:73], v[160:163], v[234:237], v[70:73]
	v_mfma_f32_16x16x32_bf16 v[66:69], v[168:171], v[234:237], v[66:69]
	v_mfma_f32_16x16x32_bf16 v[118:121], v[164:167], v[206:209], v[118:121]
	v_mfma_f32_16x16x32_bf16 v[114:117], v[172:175], v[206:209], v[114:117]
	v_mfma_f32_16x16x32_bf16 v[102:105], v[164:167], v[222:225], v[102:105]
	v_mfma_f32_16x16x32_bf16 v[98:101], v[172:175], v[222:225], v[98:101]
	v_mfma_f32_16x16x32_bf16 v[86:89], v[164:167], v[230:233], v[86:89]
	v_mfma_f32_16x16x32_bf16 v[82:85], v[172:175], v[230:233], v[82:85]
	v_mfma_f32_16x16x32_bf16 v[70:73], v[164:167], v[238:241], v[70:73]
	v_mfma_f32_16x16x32_bf16 v[66:69], v[172:175], v[238:241], v[66:69]
	s_setprio 0
	s_barrier
; #define PG8_STAGE(bufoff, gbase, voff) do { _Pragma("unroll") for (int _i = 0; _i < 2; ++_i) \
;         __builtin_amdgcn_global_load_lds((const unsigned*)((const char*)(gbase) + (voff)[_i]), (PG8_LAS unsigned*)(lds + (bufoff) + ldsw + _i * 8192), 16, 0, 0); } while (0)
; #define PG8_LDA(dst, b, h) do { _Pragma("unroll") for (int m = 0; m < 4; ++m) _Pragma("unroll") for (int k = 0; k < 2; ++k) dst[m][k] = *(const PG8_LAS bf16x8*)(lds + PG8_SA(b, h) + aoff + m * 2048 + k * 1024); } while (0)
; #define PG8_MMA(ai, bj, At, Bt) do { __builtin_amdgcn_s_setprio(1); _Pragma("unroll") for (int m = 0; m < 4; ++m) _Pragma("unroll") for (int n = 0; n < 2; ++n) _Pragma("unroll") for (int k = 0; k < 2; ++k) \
;         acc[ai][bj][m][n] = __builtin_amdgcn_mfma_f32_16x16x32_bf16(Bt[n][k], At[m][k], acc[ai][bj][m][n], 0, 0, 0); __builtin_amdgcn_s_setprio(0); } while (0)
; #define PG8_WAIT_V(n) asm volatile("s_waitcnt vmcnt(" #n ")" ::: "memory")
; #define PG8_WAIT_L(n) asm volatile("s_waitcnt lgkmcnt(" #n ")" ::: "memory")
; #define PG8_BAR __builtin_amdgcn_s_barrier()
; #define PG8_SCHED __builtin_amdgcn_sched_barrier(0)
; template <class Epi, class Sched, bool ALIGN_EPI, int LMASK = -1, int LMASKB = LMASK>
; __device__ __forceinline__ void gemm_phase(PG8_LAS unsigned char* lds, const Gemm g, const Sched& S, const Epi& E) {
;     ...
;             PG8_LDA(At, 1, 1); PG8_STAGE(PG8_SB(1, 0), b3, voffB); PG8_STAGE(PG8_SB(1, 1), b3 + hstepB, voffB); PG8_STAGE(PG8_SA(1, 0), a3, voffA);
;             PG8_WAIT_V(8); PG8_WAIT_L(0); PG8_BAR; PG8_MMA(1, 0, At, B0); PG8_MMA(1, 1, At, B1); PG8_BAR; PG8_SCHED;
;         }
;         if constexpr (ALIGN_EPI) { if (wr == 0) PG8_BAR; }
;         E(acc, cur, wr, wc, fr, fq);
;         if (!has_next) break;
	s_add_i32 s30, s51, s38
	v_lshl_add_u64 v[146:147], v[146:147], 0, s[80:81]
	s_mov_b32 m0, s30
	ds_read_b128 v[188:191], v151 offset:49152
	ds_read_b128 v[206:209], v151 offset:50176
	ds_read_b128 v[218:221], v151 offset:51200
	ds_read_b128 v[222:225], v151 offset:52224
	ds_read_b128 v[226:229], v151 offset:53248
	ds_read_b128 v[230:233], v151 offset:54272
	ds_read_b128 v[234:237], v151 offset:55296
	ds_read_b128 v[238:241], v151 offset:56320
	global_load_lds_dwordx4 v[146:147], off
	s_add_i32 m0, s30, 0x2000
	s_add_u32 s2, s2, 0x400800
	v_lshl_add_u64 v[146:147], v[176:177], 0, s[80:81]
	s_addc_u32 s3, s3, 0
	s_add_i32 s30, s52, s38
	global_load_lds_dwordx4 v[146:147], off
	v_lshl_add_u64 v[146:147], s[2:3], 0, v[134:135]
	s_mov_b32 m0, s30
	s_nop 0
	global_load_lds_dwordx4 v[146:147], off
	v_lshl_add_u64 v[146:147], s[2:3], 0, v[136:137]
	s_add_i32 m0, s30, 0x2000
	s_nop 0
	global_load_lds_dwordx4 v[146:147], off
	v_lshl_add_u64 v[146:147], v[194:195], 0, s[80:81]
	s_mov_b32 m0, s41
	s_nop 0
	global_load_lds_dwordx4 v[146:147], off
	v_lshl_add_u64 v[146:147], v[210:211], 0, s[80:81]
	s_mov_b32 m0, s42
	s_nop 0
	global_load_lds_dwordx4 v[146:147], off
	s_waitcnt vmcnt(8)
	s_waitcnt lgkmcnt(0)
	s_barrier
	s_setprio 1
	v_mfma_f32_16x16x32_bf16 v[62:65], v[130:133], v[188:191], v[62:65]
	v_mfma_f32_16x16x32_bf16 v[58:61], v[152:155], v[188:191], v[58:61]
	v_mfma_f32_16x16x32_bf16 v[46:49], v[130:133], v[218:221], v[46:49]
	v_mfma_f32_16x16x32_bf16 v[42:45], v[152:155], v[218:221], v[42:45]
	v_mfma_f32_16x16x32_bf16 v[30:33], v[130:133], v[226:229], v[30:33]
	v_mfma_f32_16x16x32_bf16 v[26:29], v[152:155], v[226:229], v[26:29]
	v_mfma_f32_16x16x32_bf16 v[14:17], v[130:133], v[234:237], v[14:17]
	v_mfma_f32_16x16x32_bf16 v[10:13], v[152:155], v[234:237], v[10:13]
	v_mfma_f32_16x16x32_bf16 v[62:65], v[142:145], v[206:209], v[62:65]
	v_mfma_f32_16x16x32_bf16 v[58:61], v[156:159], v[206:209], v[58:61]
	v_mfma_f32_16x16x32_bf16 v[46:49], v[142:145], v[222:225], v[46:49]
	v_mfma_f32_16x16x32_bf16 v[42:45], v[156:159], v[222:225], v[42:45]
	v_mfma_f32_16x16x32_bf16 v[30:33], v[142:145], v[230:233], v[30:33]
	v_mfma_f32_16x16x32_bf16 v[26:29], v[156:159], v[230:233], v[26:29]
	v_mfma_f32_16x16x32_bf16 v[14:17], v[142:145], v[238:241], v[14:17]
	v_mfma_f32_16x16x32_bf16 v[10:13], v[156:159], v[238:241], v[10:13]
	s_setprio 0
	s_setprio 1
	v_mfma_f32_16x16x32_bf16 v[54:57], v[160:163], v[188:191], v[54:57]
	v_mfma_f32_16x16x32_bf16 v[50:53], v[168:171], v[188:191], v[50:53]
	v_mfma_f32_16x16x32_bf16 v[38:41], v[160:163], v[218:221], v[38:41]
	v_mfma_f32_16x16x32_bf16 v[34:37], v[168:171], v[218:221], v[34:37]
	v_mfma_f32_16x16x32_bf16 v[22:25], v[160:163], v[226:229], v[22:25]
	v_mfma_f32_16x16x32_bf16 v[18:21], v[168:171], v[226:229], v[18:21]
	v_mfma_f32_16x16x32_bf16 v[6:9], v[160:163], v[234:237], v[6:9]
	v_mfma_f32_16x16x32_bf16 v[2:5], v[168:171], v[234:237], v[2:5]
	v_mfma_f32_16x16x32_bf16 v[54:57], v[164:167], v[206:209], v[54:57]
	v_mfma_f32_16x16x32_bf16 v[50:53], v[172:175], v[206:209], v[50:53]
	v_mfma_f32_16x16x32_bf16 v[38:41], v[164:167], v[222:225], v[38:41]
	v_mfma_f32_16x16x32_bf16 v[34:37], v[172:175], v[222:225], v[34:37]
	v_mfma_f32_16x16x32_bf16 v[22:25], v[164:167], v[230:233], v[22:25]
	v_mfma_f32_16x16x32_bf16 v[18:21], v[172:175], v[230:233], v[18:21]
	v_mfma_f32_16x16x32_bf16 v[6:9], v[164:167], v[238:241], v[6:9]
	v_mfma_f32_16x16x32_bf16 v[2:5], v[172:175], v[238:241], v[2:5]
	s_setprio 0
	s_barrier
	s_add_i32 s50, s50, 2
	s_add_u32 s28, s28, 0x1000
	s_addc_u32 s29, s29, 0
	s_add_u32 s48, s48, 0x1000
	s_addc_u32 s49, s49, 0
	s_cmpk_gt_u32 s50, 0xfd
	s_cbranch_scc0 .LBB0_761
	s_and_b64 vcc, exec, s[14:15]
	s_cbranch_vccz .LBB0_764
	s_barrier
